# hand-written s5_assemble_w and GLA state scan (all chain loads in flight); gla output pass loads chunk states with the other operands
# speedup vs baseline: 1.0220x; 1.0086x over previous
; #define LAS __attribute__((address_space(3)))
; template <int MODE>
; __device__ __forceinline__ void gla_item(const int TID, const Params& p, int l, int ci, int head, LAS unsigned char* lds, const float (&wg)[2][16], const float (&bg)[2], const float (&ngv)[16]) {
;     ...
; #pragma unroll
;       for (int i = 0; i < 4; ++i) { const int e = (i * 512 + tid) * 4; *(LAS f32x4*)(bfs + e) = gbv[i]; }
;       __syncthreads();
;     }
;     LAS bf16_t* vT = (LAS bf16_t*)(lds + GL_VT);
;     { const int r = tid >> 3, k8 = (tid & 7) * 8; const bool ok = r >= rmin;
;       if (!ok) { kw = (u32x4){0u, 0u, 0u, 0u}; qw = kw; }
;       float qv[8], kv[8];
; #pragma unroll
;       for (int i = 0; i < 4; ++i) { qv[2 * i] = bflo(qw[i]); qv[2 * i + 1] = bfhi(qw[i]); kv[2 * i] = bflo(kw[i]); kv[2 * i + 1] = bfhi(kw[i]); }
;       if (MODE == 0) { LAS bf16_t* kd0 = (LAS bf16_t*)(lds + GL_QE0); LAS bf16_t* kd1 = (LAS bf16_t*)(lds + GL_QE1);
; #pragma unroll
;           for (int i = 0; i < 8; ++i) { const int kk = k8 + i; kd0[kk * GLD + SWZ(kk, r)] = f2bf(kv[i] * __expf(bfs[63 * 64 + kk] - bfs[r * 64 + kk])); kd1[kk * GLD + SWZ(kk, r)] = f2bf(kv[i] * __expf(bbs[kk] - bbs[r * 64 + kk])); }
;       } else { LAS bf16_t* qe0 = (LAS bf16_t*)(lds + GL_QE0); LAS bf16_t* qe1 = (LAS bf16_t*)(lds + GL_QE1); LAS bf16_t* ke0 = (LAS bf16_t*)(lds + GL_KE0); LAS bf16_t* ke1 = (LAS bf16_t*)(lds + GL_KE1);
;           u32x4 a, b2, c2, d2;
; #pragma unroll
;           for (int i = 0; i < 4; ++i) { const int kk = k8 + 2 * i; const float f0 = bfs[r * 64 + kk], f1 = bfs[r * 64 + kk + 1], g0 = bbs[r * 64 + kk], g1 = bbs[r * 64 + kk + 1];
;               a[i] = cvt_pk_bf16(qv[2 * i] * 0.125f * __expf(f0), qv[2 * i + 1] * 0.125f * __expf(f1)); b2[i] = cvt_pk_bf16(qv[2 * i] * 0.125f * __expf(g0), qv[2 * i + 1] * 0.125f * __expf(g1));
;               c2[i] = cvt_pk_bf16(kv[2 * i] * __expf(-f0), kv[2 * i + 1] * __expf(-f1)); d2[i] = cvt_pk_bf16(kv[2 * i] * __expf(-g0), kv[2 * i + 1] * __expf(-g1)); }
;           *(LAS u32x4*)(qe0 + r * GLD + k8) = a; *(LAS u32x4*)(qe1 + r * GLD + k8) = b2; *(LAS u32x4*)(ke0 + r * GLD + k8) = c2; *(LAS u32x4*)(ke1 + r * GLD + k8) = d2; }
; #pragma unroll
;       for (int hh = 0; hh < 2; ++hh) { const int v8 = ((tid & 7) + 8 * hh) * 8; u32x4 vw = (u32x4){0u, 0u, 0u, 0u};
;           if (ok) vw = vwp[hh];
; #pragma unroll
.LBB0_340:
	v_lshl_add_u64 v[22:23], s[28:29], 0, v[72:73]
	s_lshl_b32 s1, s21, 6
	v_lshl_add_u64 v[24:25], s[28:29], 0, v[70:71]
	flat_load_dwordx4 v[38:41], v[22:23]
	flat_load_dwordx4 v[42:45], v[24:25]
	v_lshl_add_u64 v[22:23], s[28:29], 0, v[68:69]
	s_add_i32 s1, s1, s23
	v_lshl_add_u64 v[24:25], s[28:29], 0, v[66:67]
	flat_load_dwordx4 v[76:79], v[22:23]
	flat_load_dwordx4 v[122:125], v[24:25]
	s_and_b32 s10, s0, 3
	s_sub_i32 s1, s1, 48
	s_cmp_eq_u32 s21, 0
	s_cselect_b32 s21, 48, 0
	v_max_i32_e32 v0, s21, v13
	v_mov_b64_e32 v[22:23], s[2:3]
	v_add_u32_e32 v0, s1, v0
	s_lshl_b32 s24, s10, 7
	v_mad_i64_i32 v[22:23], s[8:9], v0, s4, v[22:23]
	v_mov_b32_e32 v75, v183
	v_lshl_add_u64 v[24:25], v[22:23], 0, s[24:25]
	v_lshl_add_u64 v[24:25], v[24:25], 0, v[74:75]
	flat_load_dwordx4 v[126:129], v[24:25] offset:2048
	flat_load_dwordx4 v[130:133], v[24:25] offset:2560
	s_mov_b32 s9, s25
	s_lshl_b32 s8, s10, 8
	v_lshl_add_u64 v[22:23], v[22:23], 0, s[8:9]
	v_lshl_add_u64 v[24:25], v[22:23], 0, v[182:183]
	s_mov_b64 s[8:9], 0x1000
	v_lshl_add_u64 v[134:135], v[24:25], 0, s[8:9]
	s_movk_i32 s8, 0x1000
	v_add_co_u32_e32 v24, vcc, s8, v24
	v_add_u32_e32 v0, 0, v146
	v_lshl_add_u64 v[22:23], v[22:23], 0, v[74:75]
	v_addc_co_u32_e32 v25, vcc, 0, v25, vcc
	flat_load_dwordx4 v[26:29], v[24:25]
	flat_load_dwordx4 v[30:33], v[22:23] offset:3200
	flat_load_dwordx4 v[34:37], v[22:23] offset:3072
	s_nop 0
	flat_load_dwordx4 v[22:25], v[134:135] offset:16
	v_add_u32_e32 v166, 0x50104000, v64
	v_add_u32_e32 v167, 0x50104000, v62
	v_add_u32_e32 v168, 0x50108000, v64
	v_add_u32_e32 v169, 0x50108000, v62
	global_load_dwordx4 v[150:153], v166, s[28:29] offset:1536
	global_load_dwordx4 v[154:157], v167, s[28:29] offset:1536
	global_load_dwordx4 v[158:161], v168, s[28:29] offset:1536
	global_load_dwordx4 v[162:165], v169, s[28:29] offset:1536
	s_waitcnt lgkmcnt(0)
	s_barrier
	v_cmp_gt_i32_e32 vcc, s21, v13
	s_mov_b32 s8, 0x50104000
	s_waitcnt vmcnt(0)
	ds_write_b128 v0, v[38:41] offset:16384
	ds_write_b128 v0, v[42:45] offset:24576
	ds_write_b128 v0, v[76:79] offset:32768
	ds_write_b128 v0, v[122:125] offset:40960
	s_waitcnt lgkmcnt(0)
	s_barrier
	ds_read2st64_b64 v[38:41], v87 offset0:32 offset1:64
	v_add_u32_e32 v0, 8, v87
	s_waitcnt lgkmcnt(0)
	v_mul_f32_e32 v2, 0x3fb8aa3b, v38
	v_mul_f32_e32 v4, 0x3fb8aa3b, v39
	v_mul_f32_e32 v6, 0x3fb8aa3b, v40
	v_mul_f32_e32 v8, 0x3fb8aa3b, v41
	v_mul_f32_e32 v10, 0xbfb8aa3b, v38
	v_mul_f32_e32 v18, 0xbfb8aa3b, v39
	v_mul_f32_e32 v20, 0xbfb8aa3b, v40
	v_mul_f32_e32 v38, 0xbfb8aa3b, v41
	v_exp_f32_e32 v2, v2
	v_exp_f32_e32 v4, v4
	v_exp_f32_e32 v6, v6
	v_exp_f32_e32 v8, v8
	v_exp_f32_e32 v10, v10
	v_exp_f32_e32 v18, v18
	v_exp_f32_e32 v20, v20
	v_exp_f32_e32 v38, v38
	v_cndmask_b32_e64 v42, v126, 0, vcc
	v_cndmask_b32_e64 v46, v130, 0, vcc
	v_lshlrev_b32_e32 v48, 16, v42
	v_and_b32_e32 v42, 0xffff0000, v42
	v_lshlrev_b32_e32 v50, 16, v46
	v_and_b32_e32 v46, 0xffff0000, v46
	v_mul_f32_e32 v48, 0x3e000000, v48
	v_mul_f32_e32 v42, 0x3e000000, v42
	v_cndmask_b32_e64 v39, v127, 0, vcc
	v_mul_f32_e32 v10, v10, v50
	v_mul_f32_e32 v18, v18, v46
	v_mul_f32_e32 v20, v20, v50
	v_mul_f32_e32 v46, v38, v46
	v_mul_f32_e32 v2, v48, v2
	v_mul_f32_e32 v4, v42, v4
	v_mul_f32_e32 v6, v48, v6
	v_mul_f32_e32 v8, v42, v8
	v_cvt_pk_bf16_f32 v38, v2, v4
	v_cvt_pk_bf16_f32 v42, v6, v8
	v_cvt_pk_bf16_f32 v76, v10, v18
	v_cvt_pk_bf16_f32 v122, v20, v46
	ds_read2st64_b64 v[124:127], v0 offset0:32 offset1:64
	v_and_b32_e32 v2, 0xffff0000, v39
	v_lshlrev_b32_e32 v0, 16, v39
	v_mul_f32_e32 v2, 0x3e000000, v2
	v_mul_f32_e32 v0, 0x3e000000, v0
	s_waitcnt lgkmcnt(0)
	v_mul_f32_e32 v10, 0x3fb8aa3b, v125
	v_mul_f32_e32 v8, 0x3fb8aa3b, v124
	v_exp_f32_e32 v10, v10
	v_exp_f32_e32 v8, v8
	v_cndmask_b32_e64 v43, v131, 0, vcc
	v_mul_f32_e32 v18, 0xbfb8aa3b, v124
	v_mul_f32_e32 v10, v2, v10
	v_mul_f32_e32 v8, v0, v8
	v_cvt_pk_bf16_f32 v39, v8, v10
	v_mul_f32_e32 v10, 0x3fb8aa3b, v127
	v_mul_f32_e32 v8, 0x3fb8aa3b, v126
	v_exp_f32_e32 v10, v10
	v_exp_f32_e32 v8, v8
	v_lshlrev_b32_e32 v4, 16, v43
	v_and_b32_e32 v6, 0xffff0000, v43
	v_mul_f32_e32 v2, v2, v10
	v_exp_f32_e32 v18, v18
	v_mul_f32_e32 v0, v0, v8
	v_cvt_pk_bf16_f32 v43, v0, v2
	v_mul_f32_e32 v2, 0xbfb8aa3b, v125
	v_mul_f32_e32 v8, 0xbfb8aa3b, v126
	v_exp_f32_e32 v2, v2
	v_exp_f32_e32 v8, v8
	v_mul_f32_e32 v10, 0xbfb8aa3b, v127
	v_exp_f32_e32 v10, v10
	v_mul_f32_e32 v0, v18, v4
	v_mul_f32_e32 v2, v2, v6
	v_cvt_pk_bf16_f32 v77, v0, v2
	v_mul_f32_e32 v0, v8, v4
	v_mul_f32_e32 v2, v10, v6
	v_cvt_pk_bf16_f32 v123, v0, v2
	v_add_u32_e32 v0, 16, v87
	ds_read2st64_b64 v[124:127], v0 offset0:32 offset1:64
	v_cndmask_b32_e64 v40, v128, 0, vcc
	v_and_b32_e32 v2, 0xffff0000, v40
	v_lshlrev_b32_e32 v0, 16, v40
	v_mul_f32_e32 v2, 0x3e000000, v2
	s_waitcnt lgkmcnt(0)
	v_mul_f32_e32 v10, 0x3fb8aa3b, v125
	v_mul_f32_e32 v8, 0x3fb8aa3b, v124
	v_exp_f32_e32 v10, v10
	v_exp_f32_e32 v8, v8
	v_mul_f32_e32 v0, 0x3e000000, v0
	v_cndmask_b32_e64 v44, v132, 0, vcc
	v_mul_f32_e32 v10, v2, v10
	v_mul_f32_e32 v8, v0, v8
	v_cvt_pk_bf16_f32 v40, v8, v10
	v_mul_f32_e32 v10, 0x3fb8aa3b, v127
	v_mul_f32_e32 v8, 0x3fb8aa3b, v126
	v_exp_f32_e32 v10, v10
	v_exp_f32_e32 v8, v8
	v_mul_f32_e32 v18, 0xbfb8aa3b, v124
	v_lshlrev_b32_e32 v4, 16, v44
	v_mul_f32_e32 v2, v2, v10
	v_and_b32_e32 v6, 0xffff0000, v44
	v_exp_f32_e32 v18, v18
	v_mul_f32_e32 v0, v0, v8
	v_cvt_pk_bf16_f32 v44, v0, v2
	v_mul_f32_e32 v2, 0xbfb8aa3b, v125
	v_mul_f32_e32 v8, 0xbfb8aa3b, v126
	v_exp_f32_e32 v2, v2
	v_exp_f32_e32 v8, v8
	v_mul_f32_e32 v10, 0xbfb8aa3b, v127
	v_exp_f32_e32 v10, v10
	v_mul_f32_e32 v0, v18, v4
	v_mul_f32_e32 v2, v2, v6
	v_cvt_pk_bf16_f32 v78, v0, v2
	v_mul_f32_e32 v0, v8, v4
	v_mul_f32_e32 v2, v10, v6
	v_cvt_pk_bf16_f32 v124, v0, v2
	v_add_u32_e32 v0, 24, v87
	v_cndmask_b32_e64 v41, v129, 0, vcc
	ds_read2st64_b64 v[126:129], v0 offset0:32 offset1:64
	v_and_b32_e32 v2, 0xffff0000, v41
	v_lshlrev_b32_e32 v0, 16, v41
	v_mul_f32_e32 v2, 0x3e000000, v2
	v_mul_f32_e32 v0, 0x3e000000, v0
	s_waitcnt lgkmcnt(0)
; #define LAS __attribute__((address_space(3)))
; template <int MODE>
; __device__ __forceinline__ void gla_item(const int TID, const Params& p, int l, int ci, int head, LAS unsigned char* lds, const float (&wg)[2][16], const float (&bg)[2], const float (&ngv)[16]) {
;     ...
;           for (int i = 0; i < 4; ++i) { const int kk = k8 + 2 * i; const float f0 = bfs[r * 64 + kk], f1 = bfs[r * 64 + kk + 1], g0 = bbs[r * 64 + kk], g1 = bbs[r * 64 + kk + 1];
;               a[i] = cvt_pk_bf16(qv[2 * i] * 0.125f * __expf(f0), qv[2 * i + 1] * 0.125f * __expf(f1)); b2[i] = cvt_pk_bf16(qv[2 * i] * 0.125f * __expf(g0), qv[2 * i + 1] * 0.125f * __expf(g1));
;               c2[i] = cvt_pk_bf16(kv[2 * i] * __expf(-f0), kv[2 * i + 1] * __expf(-f1)); d2[i] = cvt_pk_bf16(kv[2 * i] * __expf(-g0), kv[2 * i + 1] * __expf(-g1)); }
;           *(LAS u32x4*)(qe0 + r * GLD + k8) = a; *(LAS u32x4*)(qe1 + r * GLD + k8) = b2; *(LAS u32x4*)(ke0 + r * GLD + k8) = c2; *(LAS u32x4*)(ke1 + r * GLD + k8) = d2; }
; #pragma unroll
;       for (int hh = 0; hh < 2; ++hh) { const int v8 = ((tid & 7) + 8 * hh) * 8; u32x4 vw = (u32x4){0u, 0u, 0u, 0u};
;           if (ok) vw = vwp[hh];
; #pragma unroll
;           for (int i = 0; i < 4; ++i) { vT[(v8 + 2 * i) * GLD + SWZ(v8, r)] = (bf16_t)(vw[i] & 0xffffu); vT[(v8 + 2 * i + 1) * GLD + SWZ(v8, r)] = (bf16_t)(vw[i] >> 16); } }
;     }
;     if (MODE == 1) {
;         const bf16_t* spb = (const bf16_t*)(p.ws + WS_SPB); u32x4 sv[2][2];
; #pragma unroll
;         for (int d = 0; d < 2; ++d) { const bf16_t* src = spb + ((size_t)(ci * 4 + head) * 2 + d) * 8192;
; #pragma unroll
;             for (int i = 0; i < 2; ++i) sv[d][i] = *(const u32x4*)(src + (i * 512 + tid) * 8); }
; #pragma unroll
;         for (int d = 0; d < 2; ++d) { LAS bf16_t* sp = (LAS bf16_t*)(lds + (d ? GL_SP1 : GL_SP0));
; #pragma unroll
;             for (int i = 0; i < 2; ++i) { const int e = (i * 512 + tid) * 8; *(LAS u32x4*)(sp + (e >> 6) * GLD + (e & 63)) = sv[d][i]; } }
;     }
;     __syncthreads();
;     if (MODE == 0) {
;         float* ds = (float*)(p.ws + WS_DS); float* dec = (float*)(p.ws + WS_DECAY);
;         if (tid < 128) { const int d = tid >> 6, kk = tid & 63; dec[((size_t)(ci * 4 + head) * 2 + d) * 64 + kk] = __expf(d == 0 ? bfs[63 * 64 + kk] : bbs[kk]); }
; #pragma unroll
	v_mul_f32_e32 v10, 0x3fb8aa3b, v127
	v_mul_f32_e32 v8, 0x3fb8aa3b, v126
	v_exp_f32_e32 v10, v10
	v_exp_f32_e32 v8, v8
	v_cndmask_b32_e64 v45, v133, 0, vcc
	v_lshlrev_b32_e32 v4, 16, v45
	v_mul_f32_e32 v10, v2, v10
	v_mul_f32_e32 v8, v0, v8
	v_cvt_pk_bf16_f32 v41, v8, v10
	v_mul_f32_e32 v10, 0x3fb8aa3b, v129
	v_mul_f32_e32 v8, 0x3fb8aa3b, v128
	v_exp_f32_e32 v10, v10
	v_exp_f32_e32 v8, v8
	v_and_b32_e32 v6, 0xffff0000, v45
	v_mul_f32_e32 v18, 0xbfb8aa3b, v126
	v_mul_f32_e32 v2, v2, v10
	v_mul_f32_e32 v0, v0, v8
	v_cvt_pk_bf16_f32 v45, v0, v2
	v_mul_f32_e32 v2, 0xbfb8aa3b, v127
	v_exp_f32_e32 v18, v18
	v_exp_f32_e32 v2, v2
	v_mul_f32_e32 v8, 0xbfb8aa3b, v128
	v_mul_f32_e32 v10, 0xbfb8aa3b, v129
	v_exp_f32_e32 v8, v8
	v_exp_f32_e32 v10, v10
	v_mul_f32_e32 v0, v18, v4
	v_mul_f32_e32 v2, v2, v6
	v_cvt_pk_bf16_f32 v79, v0, v2
	v_mul_f32_e32 v0, v8, v4
	v_mul_f32_e32 v2, v10, v6
	v_cvt_pk_bf16_f32 v125, v0, v2
	ds_write_b128 v84, v[38:41] offset:49152
	ds_write_b128 v84, v[42:45] offset:58368
	ds_write_b128 v85, v[76:79]
	ds_write_b128 v86, v[122:125]
	v_cndmask_b32_e64 v0, v37, 0, vcc
	v_cndmask_b32_e64 v2, v36, 0, vcc
	v_cndmask_b32_e64 v4, v35, 0, vcc
	v_cndmask_b32_e64 v6, v34, 0, vcc
	v_lshl_add_u64 v[38:39], s[28:29], 0, v[64:65]
	ds_write_b16 v90, v6
	ds_write_b16_d16_hi v90, v6 offset:144
	ds_write_b16 v90, v4 offset:288
	ds_write_b16_d16_hi v90, v4 offset:432
	ds_write_b16 v90, v2 offset:576
	ds_write_b16_d16_hi v90, v2 offset:720
	ds_write_b16 v90, v0 offset:864
	ds_write_b16_d16_hi v90, v0 offset:1008
	v_cndmask_b32_e64 v0, v33, 0, vcc
	v_cndmask_b32_e64 v2, v32, 0, vcc
	v_cndmask_b32_e64 v4, v31, 0, vcc
	v_cndmask_b32_e64 v6, v30, 0, vcc
	v_add_co_u32_e32 v30, vcc, s8, v38
	v_lshl_add_u64 v[42:43], s[28:29], 0, v[62:63]
	s_nop 0
	v_addc_co_u32_e32 v31, vcc, 0, v39, vcc
	v_add_co_u32_e32 v34, vcc, s8, v42
	s_mov_b32 s8, 0x50108000
	s_nop 0
	v_addc_co_u32_e32 v35, vcc, 0, v43, vcc
	v_add_co_u32_e32 v38, vcc, s8, v38
	ds_write_b16 v90, v6 offset:9216
	ds_write_b16_d16_hi v90, v6 offset:9360
	ds_write_b16 v90, v4 offset:9504
	ds_write_b16_d16_hi v90, v4 offset:9648
	ds_write_b16 v90, v2 offset:9792
	ds_write_b16_d16_hi v90, v2 offset:9936
	ds_write_b16 v90, v0 offset:10080
	ds_write_b16_d16_hi v90, v0 offset:10224
	v_addc_co_u32_e32 v39, vcc, 0, v39, vcc
	v_add_co_u32_e32 v42, vcc, s8, v42
	s_nop 1
	v_addc_co_u32_e32 v43, vcc, 0, v43, vcc
	v_add_u32_e32 v0, v81, v82
	v_and_b32_e32 v4, 64, v225
	v_add_u32_e32 v4, 64, v4
	s_waitcnt vmcnt(0) lgkmcnt(0)
	ds_write_b128 v0, v[150:153]
	v_add_u32_e32 v0, v81, v88
	ds_write_b128 v0, v[154:157]
	v_add_u32_e32 v0, v83, v82
	ds_write_b128 v0, v[158:161]
	v_add_u32_e32 v0, v83, v88
	ds_write_b128 v0, v[162:165]
	s_waitcnt lgkmcnt(0)
	s_barrier
	ds_read_b128 v[30:33], v89 offset:49152
	ds_read_b128 v[34:37], v89 offset:49216
	ds_read_b128 v[38:41], v91
	ds_read_b128 v[42:45], v91 offset:64
	s_waitcnt lgkmcnt(1)
	v_mfma_f32_16x16x32_bf16 v[30:33], v[30:33], v[38:41], 0
	ds_read_b128 v[38:41], v89 offset:58368
	s_waitcnt lgkmcnt(1)
	v_mfma_f32_16x16x32_bf16 v[30:33], v[34:37], v[42:45], v[30:33]
	ds_read_b128 v[34:37], v89 offset:58432
	ds_read_b128 v[42:45], v92
	ds_read_b128 v[76:79], v92 offset:64
	s_waitcnt lgkmcnt(1)
	v_mfma_f32_16x16x32_bf16 v[38:41], v[38:41], v[42:45], 0
	s_nop 2
	v_cndmask_b32_e64 v0, v30, 0, s[38:39]
	s_waitcnt lgkmcnt(0)
	v_mfma_f32_16x16x32_bf16 v[34:37], v[34:37], v[76:79], v[38:41]
	s_nop 7
	v_cndmask_b32_e64 v2, v34, 0, s[40:41]
	v_add_f32_e32 v0, v0, v2
	v_cvt_pk_bf16_f32 v0, v0, v183
	ds_write_b16 v106, v0
	v_cndmask_b32_e64 v0, v31, 0, s[42:43]
	v_cndmask_b32_e64 v2, 0, v35, s[38:39]
	v_add_f32_e32 v0, v0, v2
	v_cvt_pk_bf16_f32 v0, v0, v183
	ds_write_b16 v106, v0 offset:144
	v_cndmask_b32_e64 v0, v32, 0, s[44:45]
	v_cndmask_b32_e64 v2, v36, 0, s[46:47]
	v_add_f32_e32 v0, v0, v2
	v_cvt_pk_bf16_f32 v0, v0, v183
	ds_write_b16 v106, v0 offset:288
	v_cndmask_b32_e64 v0, v33, 0, s[48:49]
	v_cndmask_b32_e64 v2, v37, 0, s[50:51]
	v_add_f32_e32 v0, v0, v2
	v_cvt_pk_bf16_f32 v0, v0, v183
	ds_write_b16 v106, v0 offset:432
	ds_read_b128 v[30:33], v89 offset:49152
	ds_read_b128 v[34:37], v89 offset:49216
	ds_read_b128 v[38:41], v93
	ds_read_b128 v[42:45], v93 offset:64
	s_waitcnt lgkmcnt(1)
	v_mfma_f32_16x16x32_bf16 v[30:33], v[30:33], v[38:41], 0
	ds_read_b128 v[38:41], v89 offset:58368
	s_waitcnt lgkmcnt(1)
	v_mfma_f32_16x16x32_bf16 v[30:33], v[34:37], v[42:45], v[30:33]
	ds_read_b128 v[34:37], v89 offset:58432
	ds_read_b128 v[42:45], v94
	ds_read_b128 v[76:79], v94 offset:64
	s_waitcnt lgkmcnt(1)
	v_mfma_f32_16x16x32_bf16 v[38:41], v[38:41], v[42:45], 0
	s_nop 2
	v_cndmask_b32_e64 v0, v30, 0, s[52:53]
	s_waitcnt lgkmcnt(0)
	v_mfma_f32_16x16x32_bf16 v[34:37], v[34:37], v[76:79], v[38:41]
	s_nop 7
	v_cndmask_b32_e64 v2, v34, 0, s[54:55]
	v_add_f32_e32 v0, v0, v2
	v_cvt_pk_bf16_f32 v0, v0, v183
	ds_write_b16 v107, v0
	v_cndmask_b32_e64 v0, v31, 0, s[56:57]
	v_cndmask_b32_e64 v2, 0, v35, s[52:53]
	v_add_f32_e32 v0, v0, v2
	v_cvt_pk_bf16_f32 v0, v0, v183
	ds_write_b16 v107, v0 offset:144
	v_cndmask_b32_e64 v0, v32, 0, s[58:59]
	v_cndmask_b32_e64 v2, v36, 0, s[60:61]
	v_add_f32_e32 v0, v0, v2
	v_cvt_pk_bf16_f32 v0, v0, v183
	ds_write_b16 v107, v0 offset:288
	v_cndmask_b32_e64 v0, v33, 0, s[62:63]
	v_cndmask_b32_e64 v2, v37, 0, s[64:65]
	v_add_f32_e32 v0, v0, v2
	v_cvt_pk_bf16_f32 v0, v0, v183
	ds_write_b16 v107, v0 offset:432
	s_waitcnt lgkmcnt(0)
	s_barrier
; #define LAS __attribute__((address_space(3)))
; template <int MODE>
; __device__ __forceinline__ void gla_item(const int TID, const Params& p, int l, int ci, int head, LAS unsigned char* lds, const float (&wg)[2][16], const float (&bg)[2], const float (&ngv)[16]) {
;     ...
;     LAS float* os = (LAS float*)(lds + GL_OS);
;     { const int it = wid >> 1; const LAS bf16_t* sp0 = (const LAS bf16_t*)(lds + GL_SP0); const LAS bf16_t* sp1 = (const LAS bf16_t*)(lds + GL_SP1);
; #pragma unroll
;       for (int t4 = 0; t4 < 4; ++t4) { const int vt = (wid & 1) * 4 + t4; f32x4 acc = (f32x4){0.f, 0.f, 0.f, 0.f};
;           acc = mma_lds_sw(acc, att + it * 16 * GLD, -1, vT + vt * 16 * GLD, vt * 16, GLD, 2, lane); acc = mma_lds(acc, qe0 + it * 16 * GLD, sp0 + vt * 16 * GLD, GLD, 2, lane); acc = mma_lds(acc, qe1 + it * 16 * GLD, sp1 + vt * 16 * GLD, GLD, 2, lane);
; #pragma unroll
;           for (int j = 0; j < 4; ++j) os[(it * 16 + (lane >> 4) * 4 + j) * 132 + vt * 16 + (lane & 15)] = acc[j]; } }
;     __syncthreads();
;     { const int r = tid >> 3, v0 = (tid & 7) * 16; float o[16]; float ss = 0.f;
; #pragma unroll
;       for (int i = 0; i < 16; ++i) { o[i] = os[r * 132 + v0 + i]; ss += o[i] * o[i]; }
;       ss += __shfl_xor(ss, 1); ss += __shfl_xor(ss, 2); ss += __shfl_xor(ss, 4);
;       const float rs = rsqrtf(ss * (1.0f / 128.0f) + 1e-6f);
	ds_read_b128 v[30:33], v108
	ds_read_b128 v[34:37], v109
	ds_read_b128 v[38:41], v110
	s_waitcnt lgkmcnt(1)
	v_mfma_f32_16x16x32_bf16 v[30:33], v[30:33], v[34:37], 0
	ds_read_b128 v[34:37], v111
	ds_read_b128 v[42:45], v89 offset:49152
	v_add_u32_e32 v0, v97, v98
	v_xor_b32_e32 v2, 1, v225
	s_waitcnt lgkmcnt(1)
	v_mfma_f32_16x16x32_bf16 v[30:33], v[38:41], v[34:37], v[30:33]
	ds_read_b128 v[34:37], v89 offset:49216
	ds_read_b128 v[38:41], v95
	ds_read_b128 v[76:79], v95 offset:64
	v_cmp_lt_i32_e32 vcc, v2, v4
	s_waitcnt lgkmcnt(1)
	v_mfma_f32_16x16x32_bf16 v[30:33], v[42:45], v[38:41], v[30:33]
	ds_read_b128 v[38:41], v89 offset:58368
	v_cndmask_b32_e32 v2, v225, v2, vcc
	v_lshlrev_b32_e32 v2, 2, v2
	s_waitcnt lgkmcnt(1)
	v_mfma_f32_16x16x32_bf16 v[30:33], v[34:37], v[76:79], v[30:33]
	ds_read_b128 v[34:37], v89 offset:58432
	ds_read_b128 v[42:45], v96
	ds_read_b128 v[76:79], v96 offset:64
	s_waitcnt lgkmcnt(1)
	v_mfma_f32_16x16x32_bf16 v[30:33], v[38:41], v[42:45], v[30:33]
	s_waitcnt lgkmcnt(0)
	v_mfma_f32_16x16x32_bf16 v[30:33], v[34:37], v[76:79], v[30:33]
	s_nop 7
	ds_write2_b32 v0, v30, v31 offset1:132
	v_add_u32_e32 v0, 0x400, v0
	ds_write2_b32 v0, v32, v33 offset0:8 offset1:140
	ds_read_b128 v[30:33], v108
	ds_read_b128 v[34:37], v110
	ds_read_b128 v[38:41], v112
	ds_read_b128 v[42:45], v113
	s_waitcnt lgkmcnt(1)
	v_mfma_f32_16x16x32_bf16 v[30:33], v[30:33], v[38:41], 0
	ds_read_b128 v[38:41], v89 offset:49152
	v_add_u32_e32 v0, 0x400, v114
	s_waitcnt lgkmcnt(1)
	v_mfma_f32_16x16x32_bf16 v[30:33], v[34:37], v[42:45], v[30:33]
	ds_read_b128 v[34:37], v89 offset:49216
	ds_read_b128 v[42:45], v99
	ds_read_b128 v[76:79], v99 offset:64
	s_waitcnt lgkmcnt(1)
	v_mfma_f32_16x16x32_bf16 v[30:33], v[38:41], v[42:45], v[30:33]
	ds_read_b128 v[38:41], v89 offset:58368
	s_waitcnt lgkmcnt(1)
	v_mfma_f32_16x16x32_bf16 v[30:33], v[34:37], v[76:79], v[30:33]
	ds_read_b128 v[34:37], v89 offset:58432
	ds_read_b128 v[42:45], v100
	ds_read_b128 v[76:79], v100 offset:64
	s_waitcnt lgkmcnt(1)
	v_mfma_f32_16x16x32_bf16 v[30:33], v[38:41], v[42:45], v[30:33]
	s_waitcnt lgkmcnt(0)
	v_mfma_f32_16x16x32_bf16 v[30:33], v[34:37], v[76:79], v[30:33]
	s_nop 7
	ds_write2_b32 v114, v30, v31 offset1:132
	ds_write2_b32 v0, v32, v33 offset0:8 offset1:140
	ds_read_b128 v[30:33], v108
	ds_read_b128 v[34:37], v110
	ds_read_b128 v[38:41], v115
	ds_read_b128 v[42:45], v116
	s_waitcnt lgkmcnt(1)
	v_mfma_f32_16x16x32_bf16 v[30:33], v[30:33], v[38:41], 0
	ds_read_b128 v[38:41], v89 offset:49152
	v_add_u32_e32 v0, 0x400, v117
	s_waitcnt lgkmcnt(1)
	v_mfma_f32_16x16x32_bf16 v[30:33], v[34:37], v[42:45], v[30:33]
	ds_read_b128 v[34:37], v89 offset:49216
	ds_read_b128 v[42:45], v101
	ds_read_b128 v[76:79], v101 offset:64
	s_waitcnt lgkmcnt(1)
	v_mfma_f32_16x16x32_bf16 v[30:33], v[38:41], v[42:45], v[30:33]
	ds_read_b128 v[38:41], v89 offset:58368
	s_waitcnt lgkmcnt(1)
	v_mfma_f32_16x16x32_bf16 v[30:33], v[34:37], v[76:79], v[30:33]
	ds_read_b128 v[34:37], v89 offset:58432
	ds_read_b128 v[42:45], v102
	ds_read_b128 v[76:79], v102 offset:64
	s_waitcnt lgkmcnt(1)
	v_mfma_f32_16x16x32_bf16 v[30:33], v[38:41], v[42:45], v[30:33]
	s_waitcnt lgkmcnt(0)
	v_mfma_f32_16x16x32_bf16 v[30:33], v[34:37], v[76:79], v[30:33]
	s_nop 7
	ds_write2_b32 v117, v30, v31 offset1:132
	ds_write2_b32 v0, v32, v33 offset0:8 offset1:140
	ds_read_b128 v[30:33], v108
	ds_read_b128 v[34:37], v110
	ds_read_b128 v[38:41], v118
	ds_read_b128 v[42:45], v119
	s_waitcnt lgkmcnt(1)
	v_mfma_f32_16x16x32_bf16 v[30:33], v[30:33], v[38:41], 0
	ds_read_b128 v[38:41], v89 offset:49152
	v_add_u32_e32 v0, 0x400, v120
	s_waitcnt lgkmcnt(1)
	v_mfma_f32_16x16x32_bf16 v[30:33], v[34:37], v[42:45], v[30:33]
	ds_read_b128 v[34:37], v89 offset:49216
	ds_read_b128 v[42:45], v103
	ds_read_b128 v[76:79], v103 offset:64
	s_waitcnt lgkmcnt(1)
	v_mfma_f32_16x16x32_bf16 v[30:33], v[38:41], v[42:45], v[30:33]
	ds_read_b128 v[38:41], v89 offset:58368
	s_waitcnt lgkmcnt(1)
	v_mfma_f32_16x16x32_bf16 v[30:33], v[34:37], v[76:79], v[30:33]
	ds_read_b128 v[34:37], v89 offset:58432
	ds_read_b128 v[42:45], v104
	ds_read_b128 v[76:79], v104 offset:64
	s_waitcnt lgkmcnt(1)
	v_mfma_f32_16x16x32_bf16 v[30:33], v[38:41], v[42:45], v[30:33]
	s_waitcnt lgkmcnt(0)
	v_mfma_f32_16x16x32_bf16 v[30:33], v[34:37], v[76:79], v[30:33]
	s_nop 7
	ds_write2_b32 v120, v30, v31 offset1:132
	ds_write2_b32 v0, v32, v33 offset0:8 offset1:140
	s_waitcnt lgkmcnt(0)
	s_barrier
	ds_read_b128 v[42:45], v105
	ds_read_b128 v[38:41], v105 offset:16
	ds_read_b128 v[34:37], v105 offset:32
	ds_read_b128 v[30:33], v105 offset:48
	s_waitcnt lgkmcnt(3)
	v_mul_f32_e32 v0, v43, v43
	v_fmac_f32_e32 v0, v42, v42
	v_fmac_f32_e32 v0, v44, v44
	v_fmac_f32_e32 v0, v45, v45
	s_waitcnt lgkmcnt(2)
	v_fmac_f32_e32 v0, v38, v38
	v_fmac_f32_e32 v0, v39, v39
	v_fmac_f32_e32 v0, v40, v40
	v_fmac_f32_e32 v0, v41, v41
	s_waitcnt lgkmcnt(1)
	v_fmac_f32_e32 v0, v34, v34
	v_fmac_f32_e32 v0, v35, v35
	v_fmac_f32_e32 v0, v36, v36
	v_fmac_f32_e32 v0, v37, v37
	s_waitcnt lgkmcnt(0)
	v_fmac_f32_e32 v0, v30, v30
	v_fmac_f32_e32 v0, v31, v31
	v_fmac_f32_e32 v0, v32, v32
	v_fmac_f32_e32 v0, v33, v33
	ds_bpermute_b32 v2, v2, v0
	s_waitcnt lgkmcnt(0)
	v_add_f32_e32 v0, v0, v2
	v_xor_b32_e32 v2, 2, v225
	v_cmp_lt_i32_e32 vcc, v2, v4
	s_nop 1
	v_cndmask_b32_e32 v2, v225, v2, vcc
	v_lshlrev_b32_e32 v2, 2, v2
	ds_bpermute_b32 v2, v2, v0
	s_waitcnt lgkmcnt(0)
	v_add_f32_e32 v0, v0, v2
	v_xor_b32_e32 v2, 4, v225
	v_cmp_lt_i32_e32 vcc, v2, v4
	s_nop 1
	v_cndmask_b32_e32 v2, v225, v2, vcc
	v_lshlrev_b32_e32 v2, 2, v2
	ds_bpermute_b32 v2, v2, v0
	v_cmp_le_i32_e32 vcc, s21, v13
	s_and_saveexec_b64 s[66:67], vcc
	s_cbranch_execz .LBB0_334
; __device__ __forceinline__ unsigned cvt_pk_bf16(float lo, float hi) { unsigned r; asm volatile("v_cvt_pk_bf16_f32 %0, %1, %2" : "=v"(r) : "v"(lo), "v"(hi)); return r; }
; __device__ __forceinline__ float bflo(unsigned w) { return __uint_as_float(w << 16); }
; __device__ __forceinline__ float bfhi(unsigned w) { return __uint_as_float(w & 0xffff0000u); }
; __device__ __forceinline__ float silu(float x) { return x * sigm(x); }
; template <int MODE>
; __device__ __forceinline__ void gla_item(const int TID, const Params& p, int l, int ci, int head, LAS unsigned char* lds, const float (&wg)[2][16], const float (&bg)[2], const float (&ngv)[16]) {
;     ...
;       const float rs = rsqrtf(ss * (1.0f / 128.0f) + 1e-6f);
;       if (r >= rmin) { const size_t tok = (size_t)(tok0 + r); bf16_t* yall = (bf16_t*)(p.ws + WS_YALL);
; #pragma unroll
;           for (int hh = 0; hh < 2; ++hh) { const u32x4 gw = gwp[hh]; u32x4 w;
; #pragma unroll
;               for (int i = 0; i < 4; ++i) { const int e = hh * 8 + 2 * i; w[i] = cvt_pk_bf16(o[e] * rs * ngv[e] * silu(bflo(gw[i])), o[e + 1] * rs * ngv[e + 1] * silu(bfhi(gw[i]))); }
;               *(u32x4*)(yall + tok * D + 512 + head * 128 + v0 + hh * 8) = w; } } }
	s_waitcnt lgkmcnt(0)
	v_add_f32_e32 v0, v0, v2
	v_fmamk_f32 v0, v0, 0x3c000000, v226
	v_cmp_gt_f32_e32 vcc, s19, v0
	v_mul_f32_e32 v2, 0x4b800000, v0
	v_lshlrev_b32_e32 v46, 16, v26
	v_cndmask_b32_e32 v0, v0, v2, vcc
	v_rsq_f32_e32 v0, v0
	v_lshlrev_b32_e32 v48, 16, v27
	v_lshlrev_b32_e32 v50, 16, v28
	v_lshlrev_b32_e32 v52, 16, v29
	v_mul_f32_e32 v2, 0x45800000, v0
	v_cndmask_b32_e32 v20, v0, v2, vcc
	v_mul_f32_e32 v0, 0xbfb8aa3b, v46
	v_exp_f32_e32 v0, v0
	v_mul_f32_e32 v123, v42, v20
	v_mul_f32_e32 v43, v43, v20
	v_mul_f32_e32 v39, v39, v20
	v_add_f32_e32 v0, 1.0, v0
	v_rcp_f32_e32 v122, v0
	v_and_b32_e32 v0, 0xffff0000, v26
	v_mul_f32_e32 v4, 0xbfb8aa3b, v0
	v_exp_f32_e32 v4, v4
	v_pk_mul_f32 v[122:123], v[122:123], v[46:47]
	v_and_b32_e32 v6, 0xffff0000, v29
	v_mul_f32_e32 v2, v122, v123
	v_add_f32_e32 v4, 1.0, v4
	v_rcp_f32_e32 v42, v4
	v_add_u32_e32 v76, s1, v13
	v_ashrrev_i32_e32 v77, 31, v76
	v_lshlrev_b32_e32 v54, 16, v22
	v_pk_mul_f32 v[42:43], v[42:43], v[0:1]
	v_lshlrev_b64 v[76:77], 12, v[76:77]
	v_mul_f32_e32 v0, v42, v43
	v_cvt_pk_bf16_f32 v26, v2, v0
	v_mul_f32_e32 v0, 0xbfb8aa3b, v48
	v_exp_f32_e32 v0, v0
	v_and_b32_e32 v2, 0xffff0000, v27
	v_mul_f32_e32 v4, 0xbfb8aa3b, v2
	v_exp_f32_e32 v4, v4
	v_add_f32_e32 v0, 1.0, v0
	v_rcp_f32_e32 v42, v0
	v_mul_f32_e32 v43, v44, v20
	v_add_f32_e32 v4, 1.0, v4
	v_lshl_add_u64 v[76:77], s[94:95], 0, v[76:77]
	v_pk_mul_f32 v[42:43], v[42:43], v[48:49]
	s_lshl_b32 s24, s24, 1
	v_mul_f32_e32 v0, v42, v43
	v_rcp_f32_e32 v42, v4
	v_mul_f32_e32 v43, v45, v20
	v_and_b32_e32 v4, 0xffff0000, v28
	v_lshl_add_u64 v[76:77], v[76:77], 0, s[24:25]
	v_pk_mul_f32 v[42:43], v[42:43], v[2:3]
	v_lshl_add_u64 v[78:79], v[76:77], 0, v[182:183]
	v_mul_f32_e32 v2, v42, v43
	v_cvt_pk_bf16_f32 v27, v0, v2
	v_mul_f32_e32 v0, 0xbfb8aa3b, v50
	v_exp_f32_e32 v0, v0
	v_mul_f32_e32 v2, 0xbfb8aa3b, v4
	v_exp_f32_e32 v2, v2
	v_mul_f32_e32 v43, v38, v20
	v_add_f32_e32 v0, 1.0, v0
	v_rcp_f32_e32 v42, v0
	v_add_f32_e32 v2, 1.0, v2
	v_rcp_f32_e32 v38, v2
	s_mov_b32 s1, 0x32c60000
	v_pk_mul_f32 v[42:43], v[42:43], v[50:51]
	v_and_b32_e32 v8, 0xffff0000, v22
	v_mul_f32_e32 v0, v42, v43
	v_pk_mul_f32 v[38:39], v[38:39], v[4:5]
	v_lshlrev_b32_e32 v56, 16, v23
	v_mul_f32_e32 v2, v38, v39
	v_cvt_pk_bf16_f32 v28, v0, v2
	v_mul_f32_e32 v0, 0xbfb8aa3b, v52
	v_exp_f32_e32 v0, v0
	v_mul_f32_e32 v2, 0xbfb8aa3b, v6
	v_exp_f32_e32 v2, v2
	v_mul_f32_e32 v39, v40, v20
	v_add_f32_e32 v0, 1.0, v0
	v_rcp_f32_e32 v38, v0
	v_add_f32_e32 v2, 1.0, v2
	v_and_b32_e32 v10, 0xffff0000, v23
	v_lshlrev_b32_e32 v58, 16, v24
	v_pk_mul_f32 v[38:39], v[38:39], v[52:53]
	v_and_b32_e32 v18, 0xffff0000, v24
	v_mul_f32_e32 v0, v38, v39
	v_rcp_f32_e32 v38, v2
	v_mul_f32_e32 v39, v41, v20
	v_lshlrev_b32_e32 v60, 16, v25
	s_mov_b64 s[8:9], 0x32c60400
	v_pk_mul_f32 v[38:39], v[38:39], v[6:7]
	v_lshl_add_u64 v[76:77], v[78:79], 0, s[8:9]
	v_mul_f32_e32 v2, v38, v39
	v_cvt_pk_bf16_f32 v29, v0, v2
	v_mul_f32_e32 v0, 0xbfb8aa3b, v54
	v_exp_f32_e32 v0, v0
	v_add_co_u32_e32 v38, vcc, s1, v78
	v_mul_f32_e32 v2, 0xbfb8aa3b, v8
	s_nop 0
	v_addc_co_u32_e32 v39, vcc, 0, v79, vcc
	v_add_f32_e32 v0, 1.0, v0
	flat_store_dwordx4 v[38:39], v[26:29] offset:1024
	v_exp_f32_e32 v2, v2
	s_nop 0
	v_rcp_f32_e32 v26, v0
	v_mul_f32_e32 v27, v34, v20
	v_add_f32_e32 v2, 1.0, v2
	v_pk_mul_f32 v[26:27], v[26:27], v[54:55]
	s_nop 0
	v_mul_f32_e32 v0, v26, v27
	v_rcp_f32_e32 v26, v2
	v_mul_f32_e32 v27, v35, v20
	v_pk_mul_f32 v[26:27], v[26:27], v[8:9]
	s_nop 0
	v_mul_f32_e32 v2, v26, v27
	v_cvt_pk_bf16_f32 v22, v0, v2
	v_mul_f32_e32 v0, 0xbfb8aa3b, v56
	v_exp_f32_e32 v0, v0
	v_mul_f32_e32 v2, 0xbfb8aa3b, v10
	v_exp_f32_e32 v2, v2
	v_mul_f32_e32 v27, v36, v20
	v_add_f32_e32 v0, 1.0, v0
	v_rcp_f32_e32 v26, v0
	v_add_f32_e32 v2, 1.0, v2
	v_pk_mul_f32 v[26:27], v[26:27], v[56:57]
	s_nop 0
	v_mul_f32_e32 v0, v26, v27
	v_rcp_f32_e32 v26, v2
	v_mul_f32_e32 v27, v37, v20
	v_pk_mul_f32 v[26:27], v[26:27], v[10:11]
	s_nop 0
	v_mul_f32_e32 v2, v26, v27
	v_cvt_pk_bf16_f32 v23, v0, v2
	v_mul_f32_e32 v0, 0xbfb8aa3b, v58
	v_exp_f32_e32 v0, v0
	v_mul_f32_e32 v2, 0xbfb8aa3b, v18
	v_exp_f32_e32 v2, v2
	v_mul_f32_e32 v27, v30, v20
	v_add_f32_e32 v0, 1.0, v0
	v_rcp_f32_e32 v26, v0
	v_add_f32_e32 v2, 1.0, v2
	v_pk_mul_f32 v[26:27], v[26:27], v[58:59]
	s_nop 0
	v_mul_f32_e32 v0, v26, v27
	v_rcp_f32_e32 v26, v2
	v_mul_f32_e32 v27, v31, v20
	v_pk_mul_f32 v[26:27], v[26:27], v[18:19]
	s_nop 0
	v_mul_f32_e32 v2, v26, v27
	v_cvt_pk_bf16_f32 v24, v0, v2
	v_mul_f32_e32 v0, 0xbfb8aa3b, v60
	v_exp_f32_e32 v0, v0
	v_mul_f32_e32 v27, v32, v20
	v_add_f32_e32 v0, 1.0, v0
	v_rcp_f32_e32 v26, v0
	s_nop 0
	v_pk_mul_f32 v[26:27], v[26:27], v[60:61]
	s_nop 0
	v_mul_f32_e32 v0, v26, v27
	v_mul_f32_e32 v27, v33, v20
	v_and_b32_e32 v20, 0xffff0000, v25
	v_mul_f32_e32 v2, 0xbfb8aa3b, v20
	v_exp_f32_e32 v2, v2
	s_nop 0
	v_add_f32_e32 v2, 1.0, v2
	v_rcp_f32_e32 v26, v2
	s_nop 0
	v_pk_mul_f32 v[26:27], v[26:27], v[20:21]
	s_nop 0
	v_mul_f32_e32 v2, v26, v27
	v_cvt_pk_bf16_f32 v25, v0, v2
	flat_store_dwordx4 v[76:77], v[22:25] offset:16
	s_branch .LBB0_334

; __device__ __forceinline__ float bf2f(bf16_t b) { return __uint_as_float(((unsigned)b) << 16); }
; __device__ __forceinline__ void scans_phase(const int TID, const int BID, const Params& p, const int l, const bool do_gla) {
;     ...
;     if (do_gla) {
;         const bf16_t* ds = (const bf16_t*)(p.ws + WS_DS); const float* dec = (const float*)(p.ws + WS_DECAY); bf16_t* spb = (bf16_t*)(p.ws + WS_SPB);
;         for (int it = 0; ; ++it) {
;             int vb;
;             if (split) { if (BID >= 120) { if (it >= 8) break; vb = (BID - 120) + 136 * it; } else { vb = 1088 + BID + 120 * it; if (vb >= 1280) break; } }
;             else { vb = BID + G * it; if (vb >= 1280) break; }
;             const int e = vb * 512 + TID;
;             const int seq = e >> 16, rem = e & 65535, head = rem >> 14, d = (rem >> 13) & 1, el = rem & 8191, kk = el & 63;
;             const int cb = seq < 2 ? seq * 65 : 130 + (seq - 2) * 33, nc = seq < 2 ? 65 : 33;
;             float S = 0.f;
;             for (int s0 = 0; s0 < nc; s0 += 16) {
;                 float tm[16], dc[16];
; #pragma unroll
;                 for (int i = 0; i < 16; ++i) { const int step = s0 + i; tm[i] = 0.f; dc[i] = 1.f;
;                     { const int sc = step < nc ? step : nc - 1; const int ci = cb + (d == 0 ? sc : nc - 1 - sc); const size_t o = ((size_t)(ci * 4 + head) * 2 + d); tm[i] = bf2f(ds[o * 8192 + el]); dc[i] = dec[o * 64 + kk]; } }
.LBB0_675:
	s_cmpk_lg_i32 s96, 0x100
	s_cbranch_scc1 .Lgs_orig
	s_cmp_lt_u32 s22, 16
	s_cbranch_scc1 .LBB0_723
	s_mov_b32 s38, 0
	v_and_b32_e32 v155, 63, v194
	v_lshlrev_b32_e32 v155, 2, v155
.Lgs_next:
	s_cmp_lt_u32 s22, 0x78
	s_cbranch_scc1 .Lgs_low
	s_cmp_ge_u32 s38, 6
	s_cbranch_scc1 .LBB0_723
	s_mul_i32 s39, s38, 0x88
	s_add_i32 s39, s39, s22
	s_sub_i32 s39, s39, 0x78
	s_branch .Lgs_have
.Lgs_low:
	s_mul_i32 s39, s38, 0x68
	s_sub_i32 s39, s39, s22
	s_add_i32 s39, s39, 0x3a7
	s_cmp_ge_u32 s39, 0x500
	s_cbranch_scc1 .LBB0_723
.Lgs_have:
	s_lshr_b32 s8, s39, 7
	s_bfe_u32 s9, s39, 0x20005
	s_bfe_u32 s10, s39, 0x10004
	s_and_b32 s11, s39, 15
	s_lshl_b32 s11, s11, 9
	v_add_u32_e32 v154, s11, v194
	v_lshlrev_b32_e32 v154, 1, v154
	s_cmp_lt_u32 s8, 2
	s_cbranch_scc0 .Lgs_short
	s_mul_i32 s23, s8, 65
	s_mov_b32 s24, 65
	s_branch .Lgs_cb
.Lgs_short:
	s_sub_i32 s23, s8, 2
	s_mul_i32 s23, s23, 33
	s_add_i32 s23, s23, 0x82
	s_mov_b32 s24, 33
.Lgs_cb:
	s_add_i32 s28, s24, -1
	s_cmp_lg_u32 s10, 0
	s_cselect_b32 s28, s28, 0
	s_add_i32 s28, s28, s23
	s_lshl_b32 s28, s28, 2
	s_add_i32 s28, s28, s9
	s_lshl_b32 s28, s28, 1
	s_add_i32 s28, s28, s10
	s_cmp_lg_u32 s10, 0
	s_mov_b32 s48, 0x20000
	s_mov_b32 s49, 0xfffe0000
	s_movk_i32 s50, 0x800
	s_movk_i32 s51, 0xf800
	s_cmp_lg_u32 s10, 0
	s_cselect_b32 s48, s49, s48
	s_cselect_b32 s50, s51, s50
	s_cselect_b32 s49, -1, 0
	s_cselect_b32 s51, -1, 0
	s_lshl_b32 s29, s28, 14
	s_add_u32 s40, s94, 0x415a0000
	s_addc_u32 s41, s95, 0
	s_add_u32 s40, s40, s29
	s_addc_u32 s41, s41, 0
	s_add_u32 s44, s94, 0x50104600
	s_addc_u32 s45, s95, 0
	s_add_u32 s44, s44, s29
	s_addc_u32 s45, s45, 0
	s_lshl_b32 s29, s28, 8
	s_add_u32 s42, s94, 0x47820000
	s_addc_u32 s43, s95, 0
	s_add_u32 s42, s42, s29
	s_addc_u32 s43, s43, 0
	global_load_ushort v20, v154, s[40:41]
	global_load_dword v85, v155, s[42:43]
	s_add_u32 s40, s40, s48
	s_addc_u32 s41, s41, s49
	s_add_u32 s42, s42, s50
	s_addc_u32 s43, s43, s51
	global_load_ushort v21, v154, s[40:41]
	global_load_dword v86, v155, s[42:43]
	s_add_u32 s40, s40, s48
	s_addc_u32 s41, s41, s49
	s_add_u32 s42, s42, s50
	s_addc_u32 s43, s43, s51
	global_load_ushort v22, v154, s[40:41]
	global_load_dword v87, v155, s[42:43]
	s_add_u32 s40, s40, s48
	s_addc_u32 s41, s41, s49
	s_add_u32 s42, s42, s50
	s_addc_u32 s43, s43, s51
	global_load_ushort v23, v154, s[40:41]
	global_load_dword v88, v155, s[42:43]
	s_add_u32 s40, s40, s48
	s_addc_u32 s41, s41, s49
	s_add_u32 s42, s42, s50
	s_addc_u32 s43, s43, s51
	global_load_ushort v24, v154, s[40:41]
	global_load_dword v89, v155, s[42:43]
	s_add_u32 s40, s40, s48
	s_addc_u32 s41, s41, s49
	s_add_u32 s42, s42, s50
	s_addc_u32 s43, s43, s51
	global_load_ushort v25, v154, s[40:41]
	global_load_dword v90, v155, s[42:43]
	s_add_u32 s40, s40, s48
	s_addc_u32 s41, s41, s49
	s_add_u32 s42, s42, s50
	s_addc_u32 s43, s43, s51
	global_load_ushort v26, v154, s[40:41]
	global_load_dword v91, v155, s[42:43]
	s_add_u32 s40, s40, s48
	s_addc_u32 s41, s41, s49
	s_add_u32 s42, s42, s50
	s_addc_u32 s43, s43, s51
	global_load_ushort v27, v154, s[40:41]
	global_load_dword v92, v155, s[42:43]
	s_add_u32 s40, s40, s48
	s_addc_u32 s41, s41, s49
	s_add_u32 s42, s42, s50
	s_addc_u32 s43, s43, s51
	global_load_ushort v28, v154, s[40:41]
	global_load_dword v93, v155, s[42:43]
	s_add_u32 s40, s40, s48
	s_addc_u32 s41, s41, s49
	s_add_u32 s42, s42, s50
	s_addc_u32 s43, s43, s51
	global_load_ushort v29, v154, s[40:41]
	global_load_dword v94, v155, s[42:43]
	s_add_u32 s40, s40, s48
	s_addc_u32 s41, s41, s49
	s_add_u32 s42, s42, s50
	s_addc_u32 s43, s43, s51
	global_load_ushort v30, v154, s[40:41]
	global_load_dword v95, v155, s[42:43]
	s_add_u32 s40, s40, s48
	s_addc_u32 s41, s41, s49
	s_add_u32 s42, s42, s50
	s_addc_u32 s43, s43, s51
	global_load_ushort v31, v154, s[40:41]
	global_load_dword v96, v155, s[42:43]
	s_add_u32 s40, s40, s48
	s_addc_u32 s41, s41, s49
	s_add_u32 s42, s42, s50
	s_addc_u32 s43, s43, s51
	global_load_ushort v32, v154, s[40:41]
	global_load_dword v97, v155, s[42:43]
	s_add_u32 s40, s40, s48
	s_addc_u32 s41, s41, s49
	s_add_u32 s42, s42, s50
	s_addc_u32 s43, s43, s51
	global_load_ushort v33, v154, s[40:41]
	global_load_dword v98, v155, s[42:43]
	s_add_u32 s40, s40, s48
	s_addc_u32 s41, s41, s49
	s_add_u32 s42, s42, s50
	s_addc_u32 s43, s43, s51
	global_load_ushort v34, v154, s[40:41]
	global_load_dword v99, v155, s[42:43]
	s_add_u32 s40, s40, s48
	s_addc_u32 s41, s41, s49
	s_add_u32 s42, s42, s50
	s_addc_u32 s43, s43, s51
	global_load_ushort v35, v154, s[40:41]
	global_load_dword v100, v155, s[42:43]
	s_add_u32 s40, s40, s48
	s_addc_u32 s41, s41, s49
	s_add_u32 s42, s42, s50
	s_addc_u32 s43, s43, s51
	global_load_ushort v36, v154, s[40:41]
	global_load_dword v101, v155, s[42:43]
	s_add_u32 s40, s40, s48
	s_addc_u32 s41, s41, s49
	s_add_u32 s42, s42, s50
	s_addc_u32 s43, s43, s51
	global_load_ushort v37, v154, s[40:41]
	global_load_dword v102, v155, s[42:43]
	s_add_u32 s40, s40, s48
	s_addc_u32 s41, s41, s49
	s_add_u32 s42, s42, s50
	s_addc_u32 s43, s43, s51
	global_load_ushort v38, v154, s[40:41]
	global_load_dword v103, v155, s[42:43]
	s_add_u32 s40, s40, s48
	s_addc_u32 s41, s41, s49
	s_add_u32 s42, s42, s50
	s_addc_u32 s43, s43, s51
	global_load_ushort v39, v154, s[40:41]
	global_load_dword v104, v155, s[42:43]
	s_add_u32 s40, s40, s48
	s_addc_u32 s41, s41, s49
	s_add_u32 s42, s42, s50
	s_addc_u32 s43, s43, s51
	global_load_ushort v40, v154, s[40:41]
	global_load_dword v105, v155, s[42:43]
	s_add_u32 s40, s40, s48
	s_addc_u32 s41, s41, s49
	s_add_u32 s42, s42, s50
	s_addc_u32 s43, s43, s51
	global_load_ushort v41, v154, s[40:41]
	global_load_dword v106, v155, s[42:43]
; __device__ __forceinline__ float bf2f(bf16_t b) { return __uint_as_float(((unsigned)b) << 16); }
; __device__ __forceinline__ void scans_phase(const int TID, const int BID, const Params& p, const int l, const bool do_gla) {
;     ...
; #pragma unroll
;                 for (int i = 0; i < 16; ++i) { const int step = s0 + i; tm[i] = 0.f; dc[i] = 1.f;
;                     { const int sc = step < nc ? step : nc - 1; const int ci = cb + (d == 0 ? sc : nc - 1 - sc); const size_t o = ((size_t)(ci * 4 + head) * 2 + d); tm[i] = bf2f(ds[o * 8192 + el]); dc[i] = dec[o * 64 + kk]; } }
	s_add_u32 s40, s40, s48
	s_addc_u32 s41, s41, s49
	s_add_u32 s42, s42, s50
	s_addc_u32 s43, s43, s51
	global_load_ushort v42, v154, s[40:41]
	global_load_dword v107, v155, s[42:43]
	s_add_u32 s40, s40, s48
	s_addc_u32 s41, s41, s49
	s_add_u32 s42, s42, s50
	s_addc_u32 s43, s43, s51
	global_load_ushort v43, v154, s[40:41]
	global_load_dword v108, v155, s[42:43]
	s_add_u32 s40, s40, s48
	s_addc_u32 s41, s41, s49
	s_add_u32 s42, s42, s50
	s_addc_u32 s43, s43, s51
	global_load_ushort v44, v154, s[40:41]
	global_load_dword v109, v155, s[42:43]
	s_add_u32 s40, s40, s48
	s_addc_u32 s41, s41, s49
	s_add_u32 s42, s42, s50
	s_addc_u32 s43, s43, s51
	global_load_ushort v45, v154, s[40:41]
	global_load_dword v110, v155, s[42:43]
	s_add_u32 s40, s40, s48
	s_addc_u32 s41, s41, s49
	s_add_u32 s42, s42, s50
	s_addc_u32 s43, s43, s51
	global_load_ushort v46, v154, s[40:41]
	global_load_dword v111, v155, s[42:43]
	s_add_u32 s40, s40, s48
	s_addc_u32 s41, s41, s49
	s_add_u32 s42, s42, s50
	s_addc_u32 s43, s43, s51
	global_load_ushort v47, v154, s[40:41]
	global_load_dword v112, v155, s[42:43]
	s_add_u32 s40, s40, s48
	s_addc_u32 s41, s41, s49
	s_add_u32 s42, s42, s50
	s_addc_u32 s43, s43, s51
	global_load_ushort v48, v154, s[40:41]
	global_load_dword v113, v155, s[42:43]
	s_add_u32 s40, s40, s48
	s_addc_u32 s41, s41, s49
	s_add_u32 s42, s42, s50
	s_addc_u32 s43, s43, s51
	global_load_ushort v49, v154, s[40:41]
	global_load_dword v114, v155, s[42:43]
	s_add_u32 s40, s40, s48
	s_addc_u32 s41, s41, s49
	s_add_u32 s42, s42, s50
	s_addc_u32 s43, s43, s51
	global_load_ushort v50, v154, s[40:41]
	global_load_dword v115, v155, s[42:43]
	s_add_u32 s40, s40, s48
	s_addc_u32 s41, s41, s49
	s_add_u32 s42, s42, s50
	s_addc_u32 s43, s43, s51
	global_load_ushort v51, v154, s[40:41]
	global_load_dword v116, v155, s[42:43]
	s_add_u32 s40, s40, s48
	s_addc_u32 s41, s41, s49
	s_add_u32 s42, s42, s50
	s_addc_u32 s43, s43, s51
	global_load_ushort v52, v154, s[40:41]
	global_load_dword v117, v155, s[42:43]
	s_add_u32 s40, s40, s48
	s_addc_u32 s41, s41, s49
	s_add_u32 s42, s42, s50
	s_addc_u32 s43, s43, s51
	s_cmp_eq_u32 s24, 33
	s_cbranch_scc1 .Lgs_loaded
	global_load_ushort v53, v154, s[40:41]
	global_load_dword v118, v155, s[42:43]
	s_add_u32 s40, s40, s48
	s_addc_u32 s41, s41, s49
	s_add_u32 s42, s42, s50
	s_addc_u32 s43, s43, s51
	global_load_ushort v54, v154, s[40:41]
	global_load_dword v119, v155, s[42:43]
	s_add_u32 s40, s40, s48
	s_addc_u32 s41, s41, s49
	s_add_u32 s42, s42, s50
	s_addc_u32 s43, s43, s51
	global_load_ushort v55, v154, s[40:41]
	global_load_dword v120, v155, s[42:43]
	s_add_u32 s40, s40, s48
	s_addc_u32 s41, s41, s49
	s_add_u32 s42, s42, s50
	s_addc_u32 s43, s43, s51
	global_load_ushort v56, v154, s[40:41]
	global_load_dword v121, v155, s[42:43]
	s_add_u32 s40, s40, s48
	s_addc_u32 s41, s41, s49
	s_add_u32 s42, s42, s50
	s_addc_u32 s43, s43, s51
	global_load_ushort v57, v154, s[40:41]
	global_load_dword v122, v155, s[42:43]
	s_add_u32 s40, s40, s48
	s_addc_u32 s41, s41, s49
	s_add_u32 s42, s42, s50
	s_addc_u32 s43, s43, s51
	global_load_ushort v58, v154, s[40:41]
	global_load_dword v123, v155, s[42:43]
	s_add_u32 s40, s40, s48
	s_addc_u32 s41, s41, s49
	s_add_u32 s42, s42, s50
	s_addc_u32 s43, s43, s51
	global_load_ushort v59, v154, s[40:41]
	global_load_dword v124, v155, s[42:43]
	s_add_u32 s40, s40, s48
	s_addc_u32 s41, s41, s49
	s_add_u32 s42, s42, s50
	s_addc_u32 s43, s43, s51
	global_load_ushort v60, v154, s[40:41]
	global_load_dword v125, v155, s[42:43]
	s_add_u32 s40, s40, s48
	s_addc_u32 s41, s41, s49
	s_add_u32 s42, s42, s50
	s_addc_u32 s43, s43, s51
	global_load_ushort v61, v154, s[40:41]
	global_load_dword v126, v155, s[42:43]
	s_add_u32 s40, s40, s48
	s_addc_u32 s41, s41, s49
	s_add_u32 s42, s42, s50
	s_addc_u32 s43, s43, s51
	global_load_ushort v62, v154, s[40:41]
	global_load_dword v127, v155, s[42:43]
	s_add_u32 s40, s40, s48
	s_addc_u32 s41, s41, s49
	s_add_u32 s42, s42, s50
	s_addc_u32 s43, s43, s51
	global_load_ushort v63, v154, s[40:41]
	global_load_dword v128, v155, s[42:43]
	s_add_u32 s40, s40, s48
	s_addc_u32 s41, s41, s49
	s_add_u32 s42, s42, s50
	s_addc_u32 s43, s43, s51
	global_load_ushort v64, v154, s[40:41]
	global_load_dword v129, v155, s[42:43]
	s_add_u32 s40, s40, s48
	s_addc_u32 s41, s41, s49
	s_add_u32 s42, s42, s50
	s_addc_u32 s43, s43, s51
	global_load_ushort v65, v154, s[40:41]
	global_load_dword v130, v155, s[42:43]
	s_add_u32 s40, s40, s48
	s_addc_u32 s41, s41, s49
	s_add_u32 s42, s42, s50
	s_addc_u32 s43, s43, s51
	global_load_ushort v66, v154, s[40:41]
	global_load_dword v131, v155, s[42:43]
	s_add_u32 s40, s40, s48
	s_addc_u32 s41, s41, s49
	s_add_u32 s42, s42, s50
	s_addc_u32 s43, s43, s51
	global_load_ushort v67, v154, s[40:41]
	global_load_dword v132, v155, s[42:43]
	s_add_u32 s40, s40, s48
	s_addc_u32 s41, s41, s49
	s_add_u32 s42, s42, s50
	s_addc_u32 s43, s43, s51
	global_load_ushort v68, v154, s[40:41]
	global_load_dword v133, v155, s[42:43]
	s_add_u32 s40, s40, s48
	s_addc_u32 s41, s41, s49
	s_add_u32 s42, s42, s50
	s_addc_u32 s43, s43, s51
	global_load_ushort v69, v154, s[40:41]
	global_load_dword v134, v155, s[42:43]
	s_add_u32 s40, s40, s48
	s_addc_u32 s41, s41, s49
	s_add_u32 s42, s42, s50
	s_addc_u32 s43, s43, s51
	global_load_ushort v70, v154, s[40:41]
	global_load_dword v135, v155, s[42:43]
	s_add_u32 s40, s40, s48
	s_addc_u32 s41, s41, s49
	s_add_u32 s42, s42, s50
	s_addc_u32 s43, s43, s51
	global_load_ushort v71, v154, s[40:41]
	global_load_dword v136, v155, s[42:43]
	s_add_u32 s40, s40, s48
	s_addc_u32 s41, s41, s49
	s_add_u32 s42, s42, s50
	s_addc_u32 s43, s43, s51
	global_load_ushort v72, v154, s[40:41]
; __device__ __forceinline__ bf16_t f2bf(float f) { return (bf16_t)(cvt_pk_bf16(f, 0.f) & 0xffffu); }
; __device__ __forceinline__ void scans_phase(const int TID, const int BID, const Params& p, const int l, const bool do_gla) {
;     ...
; #pragma unroll
;                 for (int i = 0; i < 16; ++i) { const int step = s0 + i;
;                     if (step < nc) { const int ci = cb + (d == 0 ? step : nc - 1 - step); const size_t o = ((size_t)(ci * 4 + head) * 2 + d); spb[o * 8192 + el] = f2bf(S); S = dc[i] * S + tm[i]; } }
;             }
	global_load_dword v137, v155, s[42:43]
	s_add_u32 s40, s40, s48
	s_addc_u32 s41, s41, s49
	s_add_u32 s42, s42, s50
	s_addc_u32 s43, s43, s51
	global_load_ushort v73, v154, s[40:41]
	global_load_dword v138, v155, s[42:43]
	s_add_u32 s40, s40, s48
	s_addc_u32 s41, s41, s49
	s_add_u32 s42, s42, s50
	s_addc_u32 s43, s43, s51
	global_load_ushort v74, v154, s[40:41]
	global_load_dword v139, v155, s[42:43]
	s_add_u32 s40, s40, s48
	s_addc_u32 s41, s41, s49
	s_add_u32 s42, s42, s50
	s_addc_u32 s43, s43, s51
	global_load_ushort v75, v154, s[40:41]
	global_load_dword v140, v155, s[42:43]
	s_add_u32 s40, s40, s48
	s_addc_u32 s41, s41, s49
	s_add_u32 s42, s42, s50
	s_addc_u32 s43, s43, s51
	global_load_ushort v76, v154, s[40:41]
	global_load_dword v141, v155, s[42:43]
	s_add_u32 s40, s40, s48
	s_addc_u32 s41, s41, s49
	s_add_u32 s42, s42, s50
	s_addc_u32 s43, s43, s51
	global_load_ushort v77, v154, s[40:41]
	global_load_dword v142, v155, s[42:43]
	s_add_u32 s40, s40, s48
	s_addc_u32 s41, s41, s49
	s_add_u32 s42, s42, s50
	s_addc_u32 s43, s43, s51
	global_load_ushort v78, v154, s[40:41]
	global_load_dword v143, v155, s[42:43]
	s_add_u32 s40, s40, s48
	s_addc_u32 s41, s41, s49
	s_add_u32 s42, s42, s50
	s_addc_u32 s43, s43, s51
	global_load_ushort v79, v154, s[40:41]
	global_load_dword v144, v155, s[42:43]
	s_add_u32 s40, s40, s48
	s_addc_u32 s41, s41, s49
	s_add_u32 s42, s42, s50
	s_addc_u32 s43, s43, s51
	global_load_ushort v80, v154, s[40:41]
	global_load_dword v145, v155, s[42:43]
	s_add_u32 s40, s40, s48
	s_addc_u32 s41, s41, s49
	s_add_u32 s42, s42, s50
	s_addc_u32 s43, s43, s51
	global_load_ushort v81, v154, s[40:41]
	global_load_dword v146, v155, s[42:43]
	s_add_u32 s40, s40, s48
	s_addc_u32 s41, s41, s49
	s_add_u32 s42, s42, s50
	s_addc_u32 s43, s43, s51
	global_load_ushort v82, v154, s[40:41]
	global_load_dword v147, v155, s[42:43]
	s_add_u32 s40, s40, s48
	s_addc_u32 s41, s41, s49
	s_add_u32 s42, s42, s50
	s_addc_u32 s43, s43, s51
	global_load_ushort v83, v154, s[40:41]
	global_load_dword v148, v155, s[42:43]
	s_add_u32 s40, s40, s48
	s_addc_u32 s41, s41, s49
	s_add_u32 s42, s42, s50
	s_addc_u32 s43, s43, s51
	global_load_ushort v84, v154, s[40:41]
	global_load_dword v149, v155, s[42:43]
.Lgs_loaded:
	s_waitcnt vmcnt(0)
	v_mov_b32_e32 v156, 0
	v_cvt_pk_bf16_f32 v150, v156, v183
	global_store_short v154, v150, s[44:45]
	v_lshlrev_b32_e32 v20, 16, v20
	v_fmac_f32_e32 v20, v85, v156
	s_add_u32 s44, s44, s48
	s_addc_u32 s45, s45, s49
	v_cvt_pk_bf16_f32 v151, v20, v183
	global_store_short v154, v151, s[44:45]
	v_lshlrev_b32_e32 v21, 16, v21
	v_fmac_f32_e32 v21, v86, v20
	s_add_u32 s44, s44, s48
	s_addc_u32 s45, s45, s49
	v_cvt_pk_bf16_f32 v152, v21, v183
	global_store_short v154, v152, s[44:45]
	v_lshlrev_b32_e32 v22, 16, v22
	v_fmac_f32_e32 v22, v87, v21
	s_add_u32 s44, s44, s48
	s_addc_u32 s45, s45, s49
	v_cvt_pk_bf16_f32 v153, v22, v183
	global_store_short v154, v153, s[44:45]
	v_lshlrev_b32_e32 v23, 16, v23
	v_fmac_f32_e32 v23, v88, v22
	s_add_u32 s44, s44, s48
	s_addc_u32 s45, s45, s49
	v_cvt_pk_bf16_f32 v150, v23, v183
	global_store_short v154, v150, s[44:45]
	v_lshlrev_b32_e32 v24, 16, v24
	v_fmac_f32_e32 v24, v89, v23
	s_add_u32 s44, s44, s48
	s_addc_u32 s45, s45, s49
	v_cvt_pk_bf16_f32 v151, v24, v183
	global_store_short v154, v151, s[44:45]
	v_lshlrev_b32_e32 v25, 16, v25
	v_fmac_f32_e32 v25, v90, v24
	s_add_u32 s44, s44, s48
	s_addc_u32 s45, s45, s49
	v_cvt_pk_bf16_f32 v152, v25, v183
	global_store_short v154, v152, s[44:45]
	v_lshlrev_b32_e32 v26, 16, v26
	v_fmac_f32_e32 v26, v91, v25
	s_add_u32 s44, s44, s48
	s_addc_u32 s45, s45, s49
	v_cvt_pk_bf16_f32 v153, v26, v183
	global_store_short v154, v153, s[44:45]
	v_lshlrev_b32_e32 v27, 16, v27
	v_fmac_f32_e32 v27, v92, v26
	s_add_u32 s44, s44, s48
	s_addc_u32 s45, s45, s49
	v_cvt_pk_bf16_f32 v150, v27, v183
	global_store_short v154, v150, s[44:45]
	v_lshlrev_b32_e32 v28, 16, v28
	v_fmac_f32_e32 v28, v93, v27
	s_add_u32 s44, s44, s48
	s_addc_u32 s45, s45, s49
	v_cvt_pk_bf16_f32 v151, v28, v183
	global_store_short v154, v151, s[44:45]
	v_lshlrev_b32_e32 v29, 16, v29
	v_fmac_f32_e32 v29, v94, v28
	s_add_u32 s44, s44, s48
	s_addc_u32 s45, s45, s49
	v_cvt_pk_bf16_f32 v152, v29, v183
	global_store_short v154, v152, s[44:45]
	v_lshlrev_b32_e32 v30, 16, v30
	v_fmac_f32_e32 v30, v95, v29
	s_add_u32 s44, s44, s48
	s_addc_u32 s45, s45, s49
	v_cvt_pk_bf16_f32 v153, v30, v183
	global_store_short v154, v153, s[44:45]
	v_lshlrev_b32_e32 v31, 16, v31
	v_fmac_f32_e32 v31, v96, v30
	s_add_u32 s44, s44, s48
	s_addc_u32 s45, s45, s49
	v_cvt_pk_bf16_f32 v150, v31, v183
	global_store_short v154, v150, s[44:45]
	v_lshlrev_b32_e32 v32, 16, v32
	v_fmac_f32_e32 v32, v97, v31
	s_add_u32 s44, s44, s48
	s_addc_u32 s45, s45, s49
	v_cvt_pk_bf16_f32 v151, v32, v183
	global_store_short v154, v151, s[44:45]
	v_lshlrev_b32_e32 v33, 16, v33
	v_fmac_f32_e32 v33, v98, v32
	s_add_u32 s44, s44, s48
	s_addc_u32 s45, s45, s49
	v_cvt_pk_bf16_f32 v152, v33, v183
	global_store_short v154, v152, s[44:45]
	v_lshlrev_b32_e32 v34, 16, v34
	v_fmac_f32_e32 v34, v99, v33
	s_add_u32 s44, s44, s48
	s_addc_u32 s45, s45, s49
	v_cvt_pk_bf16_f32 v153, v34, v183
	global_store_short v154, v153, s[44:45]
	v_lshlrev_b32_e32 v35, 16, v35
	v_fmac_f32_e32 v35, v100, v34
	s_add_u32 s44, s44, s48
	s_addc_u32 s45, s45, s49
	v_cvt_pk_bf16_f32 v150, v35, v183
	global_store_short v154, v150, s[44:45]
	v_lshlrev_b32_e32 v36, 16, v36
	v_fmac_f32_e32 v36, v101, v35
	s_add_u32 s44, s44, s48
	s_addc_u32 s45, s45, s49
	v_cvt_pk_bf16_f32 v151, v36, v183
	global_store_short v154, v151, s[44:45]
	v_lshlrev_b32_e32 v37, 16, v37
	v_fmac_f32_e32 v37, v102, v36
; __device__ __forceinline__ bf16_t f2bf(float f) { return (bf16_t)(cvt_pk_bf16(f, 0.f) & 0xffffu); }
; __device__ __forceinline__ void scans_phase(const int TID, const int BID, const Params& p, const int l, const bool do_gla) {
;     ...
; #pragma unroll
;                 for (int i = 0; i < 16; ++i) { const int step = s0 + i;
;                     if (step < nc) { const int ci = cb + (d == 0 ? step : nc - 1 - step); const size_t o = ((size_t)(ci * 4 + head) * 2 + d); spb[o * 8192 + el] = f2bf(S); S = dc[i] * S + tm[i]; } }
;             }
	s_add_u32 s44, s44, s48
	s_addc_u32 s45, s45, s49
	v_cvt_pk_bf16_f32 v152, v37, v183
	global_store_short v154, v152, s[44:45]
	v_lshlrev_b32_e32 v38, 16, v38
	v_fmac_f32_e32 v38, v103, v37
	s_add_u32 s44, s44, s48
	s_addc_u32 s45, s45, s49
	v_cvt_pk_bf16_f32 v153, v38, v183
	global_store_short v154, v153, s[44:45]
	v_lshlrev_b32_e32 v39, 16, v39
	v_fmac_f32_e32 v39, v104, v38
	s_add_u32 s44, s44, s48
	s_addc_u32 s45, s45, s49
	v_cvt_pk_bf16_f32 v150, v39, v183
	global_store_short v154, v150, s[44:45]
	v_lshlrev_b32_e32 v40, 16, v40
	v_fmac_f32_e32 v40, v105, v39
	s_add_u32 s44, s44, s48
	s_addc_u32 s45, s45, s49
	v_cvt_pk_bf16_f32 v151, v40, v183
	global_store_short v154, v151, s[44:45]
	v_lshlrev_b32_e32 v41, 16, v41
	v_fmac_f32_e32 v41, v106, v40
	s_add_u32 s44, s44, s48
	s_addc_u32 s45, s45, s49
	v_cvt_pk_bf16_f32 v152, v41, v183
	global_store_short v154, v152, s[44:45]
	v_lshlrev_b32_e32 v42, 16, v42
	v_fmac_f32_e32 v42, v107, v41
	s_add_u32 s44, s44, s48
	s_addc_u32 s45, s45, s49
	v_cvt_pk_bf16_f32 v153, v42, v183
	global_store_short v154, v153, s[44:45]
	v_lshlrev_b32_e32 v43, 16, v43
	v_fmac_f32_e32 v43, v108, v42
	s_add_u32 s44, s44, s48
	s_addc_u32 s45, s45, s49
	v_cvt_pk_bf16_f32 v150, v43, v183
	global_store_short v154, v150, s[44:45]
	v_lshlrev_b32_e32 v44, 16, v44
	v_fmac_f32_e32 v44, v109, v43
	s_add_u32 s44, s44, s48
	s_addc_u32 s45, s45, s49
	v_cvt_pk_bf16_f32 v151, v44, v183
	global_store_short v154, v151, s[44:45]
	v_lshlrev_b32_e32 v45, 16, v45
	v_fmac_f32_e32 v45, v110, v44
	s_add_u32 s44, s44, s48
	s_addc_u32 s45, s45, s49
	v_cvt_pk_bf16_f32 v152, v45, v183
	global_store_short v154, v152, s[44:45]
	v_lshlrev_b32_e32 v46, 16, v46
	v_fmac_f32_e32 v46, v111, v45
	s_add_u32 s44, s44, s48
	s_addc_u32 s45, s45, s49
	v_cvt_pk_bf16_f32 v153, v46, v183
	global_store_short v154, v153, s[44:45]
	v_lshlrev_b32_e32 v47, 16, v47
	v_fmac_f32_e32 v47, v112, v46
	s_add_u32 s44, s44, s48
	s_addc_u32 s45, s45, s49
	v_cvt_pk_bf16_f32 v150, v47, v183
	global_store_short v154, v150, s[44:45]
	v_lshlrev_b32_e32 v48, 16, v48
	v_fmac_f32_e32 v48, v113, v47
	s_add_u32 s44, s44, s48
	s_addc_u32 s45, s45, s49
	v_cvt_pk_bf16_f32 v151, v48, v183
	global_store_short v154, v151, s[44:45]
	v_lshlrev_b32_e32 v49, 16, v49
	v_fmac_f32_e32 v49, v114, v48
	s_add_u32 s44, s44, s48
	s_addc_u32 s45, s45, s49
	v_cvt_pk_bf16_f32 v152, v49, v183
	global_store_short v154, v152, s[44:45]
	v_lshlrev_b32_e32 v50, 16, v50
	v_fmac_f32_e32 v50, v115, v49
	s_add_u32 s44, s44, s48
	s_addc_u32 s45, s45, s49
	v_cvt_pk_bf16_f32 v153, v50, v183
	global_store_short v154, v153, s[44:45]
	v_lshlrev_b32_e32 v51, 16, v51
	v_fmac_f32_e32 v51, v116, v50
	s_add_u32 s44, s44, s48
	s_addc_u32 s45, s45, s49
	v_cvt_pk_bf16_f32 v150, v51, v183
	global_store_short v154, v150, s[44:45]
	v_lshlrev_b32_e32 v52, 16, v52
	v_fmac_f32_e32 v52, v117, v51
	s_add_u32 s44, s44, s48
	s_addc_u32 s45, s45, s49
	s_cmp_eq_u32 s24, 33
	s_cbranch_scc1 .Lgs_stored
; __device__ __forceinline__ bf16_t f2bf(float f) { return (bf16_t)(cvt_pk_bf16(f, 0.f) & 0xffffu); }
; __device__ __forceinline__ void scans_phase(const int TID, const int BID, const Params& p, const int l, const bool do_gla) {
;     ...
; #pragma unroll
;                 for (int i = 0; i < 16; ++i) { const int step = s0 + i;
;                     if (step < nc) { const int ci = cb + (d == 0 ? step : nc - 1 - step); const size_t o = ((size_t)(ci * 4 + head) * 2 + d); spb[o * 8192 + el] = f2bf(S); S = dc[i] * S + tm[i]; } }
;             }
;         }
	v_cvt_pk_bf16_f32 v151, v52, v183
	global_store_short v154, v151, s[44:45]
	v_lshlrev_b32_e32 v53, 16, v53
	v_fmac_f32_e32 v53, v118, v52
	s_add_u32 s44, s44, s48
	s_addc_u32 s45, s45, s49
	v_cvt_pk_bf16_f32 v152, v53, v183
	global_store_short v154, v152, s[44:45]
	v_lshlrev_b32_e32 v54, 16, v54
	v_fmac_f32_e32 v54, v119, v53
	s_add_u32 s44, s44, s48
	s_addc_u32 s45, s45, s49
	v_cvt_pk_bf16_f32 v153, v54, v183
	global_store_short v154, v153, s[44:45]
	v_lshlrev_b32_e32 v55, 16, v55
	v_fmac_f32_e32 v55, v120, v54
	s_add_u32 s44, s44, s48
	s_addc_u32 s45, s45, s49
	v_cvt_pk_bf16_f32 v150, v55, v183
	global_store_short v154, v150, s[44:45]
	v_lshlrev_b32_e32 v56, 16, v56
	v_fmac_f32_e32 v56, v121, v55
	s_add_u32 s44, s44, s48
	s_addc_u32 s45, s45, s49
	v_cvt_pk_bf16_f32 v151, v56, v183
	global_store_short v154, v151, s[44:45]
	v_lshlrev_b32_e32 v57, 16, v57
	v_fmac_f32_e32 v57, v122, v56
	s_add_u32 s44, s44, s48
	s_addc_u32 s45, s45, s49
	v_cvt_pk_bf16_f32 v152, v57, v183
	global_store_short v154, v152, s[44:45]
	v_lshlrev_b32_e32 v58, 16, v58
	v_fmac_f32_e32 v58, v123, v57
	s_add_u32 s44, s44, s48
	s_addc_u32 s45, s45, s49
	v_cvt_pk_bf16_f32 v153, v58, v183
	global_store_short v154, v153, s[44:45]
	v_lshlrev_b32_e32 v59, 16, v59
	v_fmac_f32_e32 v59, v124, v58
	s_add_u32 s44, s44, s48
	s_addc_u32 s45, s45, s49
	v_cvt_pk_bf16_f32 v150, v59, v183
	global_store_short v154, v150, s[44:45]
	v_lshlrev_b32_e32 v60, 16, v60
	v_fmac_f32_e32 v60, v125, v59
	s_add_u32 s44, s44, s48
	s_addc_u32 s45, s45, s49
	v_cvt_pk_bf16_f32 v151, v60, v183
	global_store_short v154, v151, s[44:45]
	v_lshlrev_b32_e32 v61, 16, v61
	v_fmac_f32_e32 v61, v126, v60
	s_add_u32 s44, s44, s48
	s_addc_u32 s45, s45, s49
	v_cvt_pk_bf16_f32 v152, v61, v183
	global_store_short v154, v152, s[44:45]
	v_lshlrev_b32_e32 v62, 16, v62
	v_fmac_f32_e32 v62, v127, v61
	s_add_u32 s44, s44, s48
	s_addc_u32 s45, s45, s49
	v_cvt_pk_bf16_f32 v153, v62, v183
	global_store_short v154, v153, s[44:45]
	v_lshlrev_b32_e32 v63, 16, v63
	v_fmac_f32_e32 v63, v128, v62
	s_add_u32 s44, s44, s48
	s_addc_u32 s45, s45, s49
	v_cvt_pk_bf16_f32 v150, v63, v183
	global_store_short v154, v150, s[44:45]
	v_lshlrev_b32_e32 v64, 16, v64
	v_fmac_f32_e32 v64, v129, v63
	s_add_u32 s44, s44, s48
	s_addc_u32 s45, s45, s49
	v_cvt_pk_bf16_f32 v151, v64, v183
	global_store_short v154, v151, s[44:45]
	v_lshlrev_b32_e32 v65, 16, v65
	v_fmac_f32_e32 v65, v130, v64
	s_add_u32 s44, s44, s48
	s_addc_u32 s45, s45, s49
	v_cvt_pk_bf16_f32 v152, v65, v183
	global_store_short v154, v152, s[44:45]
	v_lshlrev_b32_e32 v66, 16, v66
	v_fmac_f32_e32 v66, v131, v65
	s_add_u32 s44, s44, s48
	s_addc_u32 s45, s45, s49
	v_cvt_pk_bf16_f32 v153, v66, v183
	global_store_short v154, v153, s[44:45]
	v_lshlrev_b32_e32 v67, 16, v67
	v_fmac_f32_e32 v67, v132, v66
	s_add_u32 s44, s44, s48
	s_addc_u32 s45, s45, s49
	v_cvt_pk_bf16_f32 v150, v67, v183
	global_store_short v154, v150, s[44:45]
	v_lshlrev_b32_e32 v68, 16, v68
	v_fmac_f32_e32 v68, v133, v67
	s_add_u32 s44, s44, s48
	s_addc_u32 s45, s45, s49
	v_cvt_pk_bf16_f32 v151, v68, v183
	global_store_short v154, v151, s[44:45]
	v_lshlrev_b32_e32 v69, 16, v69
	v_fmac_f32_e32 v69, v134, v68
	s_add_u32 s44, s44, s48
	s_addc_u32 s45, s45, s49
	v_cvt_pk_bf16_f32 v152, v69, v183
	global_store_short v154, v152, s[44:45]
	v_lshlrev_b32_e32 v70, 16, v70
	v_fmac_f32_e32 v70, v135, v69
	s_add_u32 s44, s44, s48
	s_addc_u32 s45, s45, s49
	v_cvt_pk_bf16_f32 v153, v70, v183
	global_store_short v154, v153, s[44:45]
	v_lshlrev_b32_e32 v71, 16, v71
	v_fmac_f32_e32 v71, v136, v70
	s_add_u32 s44, s44, s48
	s_addc_u32 s45, s45, s49
	v_cvt_pk_bf16_f32 v150, v71, v183
	global_store_short v154, v150, s[44:45]
	v_lshlrev_b32_e32 v72, 16, v72
	v_fmac_f32_e32 v72, v137, v71
	s_add_u32 s44, s44, s48
	s_addc_u32 s45, s45, s49
	v_cvt_pk_bf16_f32 v151, v72, v183
	global_store_short v154, v151, s[44:45]
	v_lshlrev_b32_e32 v73, 16, v73
	v_fmac_f32_e32 v73, v138, v72
	s_add_u32 s44, s44, s48
	s_addc_u32 s45, s45, s49
	v_cvt_pk_bf16_f32 v152, v73, v183
	global_store_short v154, v152, s[44:45]
	v_lshlrev_b32_e32 v74, 16, v74
	v_fmac_f32_e32 v74, v139, v73
	s_add_u32 s44, s44, s48
	s_addc_u32 s45, s45, s49
	v_cvt_pk_bf16_f32 v153, v74, v183
	global_store_short v154, v153, s[44:45]
	v_lshlrev_b32_e32 v75, 16, v75
	v_fmac_f32_e32 v75, v140, v74
	s_add_u32 s44, s44, s48
	s_addc_u32 s45, s45, s49
	v_cvt_pk_bf16_f32 v150, v75, v183
	global_store_short v154, v150, s[44:45]
	v_lshlrev_b32_e32 v76, 16, v76
	v_fmac_f32_e32 v76, v141, v75
	s_add_u32 s44, s44, s48
	s_addc_u32 s45, s45, s49
	v_cvt_pk_bf16_f32 v151, v76, v183
	global_store_short v154, v151, s[44:45]
	v_lshlrev_b32_e32 v77, 16, v77
	v_fmac_f32_e32 v77, v142, v76
	s_add_u32 s44, s44, s48
	s_addc_u32 s45, s45, s49
	v_cvt_pk_bf16_f32 v152, v77, v183
	global_store_short v154, v152, s[44:45]
	v_lshlrev_b32_e32 v78, 16, v78
	v_fmac_f32_e32 v78, v143, v77
	s_add_u32 s44, s44, s48
	s_addc_u32 s45, s45, s49
	v_cvt_pk_bf16_f32 v153, v78, v183
	global_store_short v154, v153, s[44:45]
	v_lshlrev_b32_e32 v79, 16, v79
	v_fmac_f32_e32 v79, v144, v78
	s_add_u32 s44, s44, s48
	s_addc_u32 s45, s45, s49
	v_cvt_pk_bf16_f32 v150, v79, v183
	global_store_short v154, v150, s[44:45]
	v_lshlrev_b32_e32 v80, 16, v80
	v_fmac_f32_e32 v80, v145, v79
	s_add_u32 s44, s44, s48
	s_addc_u32 s45, s45, s49
	v_cvt_pk_bf16_f32 v151, v80, v183
	global_store_short v154, v151, s[44:45]
	v_lshlrev_b32_e32 v81, 16, v81
	v_fmac_f32_e32 v81, v146, v80
	s_add_u32 s44, s44, s48
	s_addc_u32 s45, s45, s49
	v_cvt_pk_bf16_f32 v152, v81, v183
	global_store_short v154, v152, s[44:45]
	v_lshlrev_b32_e32 v82, 16, v82
	v_fmac_f32_e32 v82, v147, v81
	s_add_u32 s44, s44, s48
	s_addc_u32 s45, s45, s49
	v_cvt_pk_bf16_f32 v153, v82, v183
	global_store_short v154, v153, s[44:45]
	v_lshlrev_b32_e32 v83, 16, v83
	v_fmac_f32_e32 v83, v148, v82
	s_add_u32 s44, s44, s48
	s_addc_u32 s45, s45, s49
	v_cvt_pk_bf16_f32 v150, v83, v183
	global_store_short v154, v150, s[44:45]
	v_lshlrev_b32_e32 v84, 16, v84
	v_fmac_f32_e32 v84, v149, v83
.Lgs_stored:
	s_add_i32 s38, s38, 1
	s_branch .Lgs_next

; __device__ __forceinline__ bf16_t f2bf(float f) { return (bf16_t)(cvt_pk_bf16(f, 0.f) & 0xffffu); }
; __device__ __forceinline__ void s5_assemble_w(const int TID, const int BID, const Params& p, int l) {
;     const f32x2* pw = (const f32x2*)(p.ws + WS_PW) + l * PWL; const float* kmat = (const float*)(p.ws + WS_KMAT);
;     bf16_t* wmat = (bf16_t*)(p.ws + WS_WMAT);
;     const float* cre = p.in[10]; const float* cim = p.in[11];
;     const size_t stride = (size_t)gridDim.x * 512;
;     for (size_t idx = (size_t)BID * 512 + TID; idx < (size_t)32 * 256 * 512; idx += stride) {
;         const int g = (int)(idx >> 17), nout = (int)(idx >> 9) & 255, k = (int)idx & 511, t = nout >> 4, c = nout & 15;
;         float val;
;         if (k < 256) { const int s = k >> 4, cp = k & 15; val = 0.f;
;             const int jf = s <= t ? t - s : 0, jb = s >= t ? s - t : 0;
;             const float kf = kmat[((((size_t)g * 2 + 0) * 16 + jf) * 16 + c) * 16 + cp], kb = kmat[((((size_t)g * 2 + 1) * 16 + jb) * 16 + c) * 16 + cp], dsk = p.in[12][l * 512 + g * 16 + c];
;             val = (s <= t ? kf : 0.f) + (s >= t ? kb : 0.f) + ((s == t && c == cp) ? dsk : 0.f);
;         } else { const int kk = k - 256, d = kk >> 7, ri = (kk >> 6) & 1, n = kk & 63, j = d == 0 ? t + 1 : 16 - t;
;             const float cr = cre[(((size_t)(l * 2 + d) * 32 + g) * 16 + c) * 64 + n], ci = cim[(((size_t)(l * 2 + d) * 32 + g) * 16 + c) * 64 + n];
;             const f32x2 pv = pw[((size_t)(g * 2 + d) * 17 + j) * 64 + n];
;             val = ri == 0 ? cr * pv.x - ci * pv.y : -(cr * pv.y + ci * pv.x); }
;         wmat[idx] = f2bf(val);
.LBB0_1012:
	s_cmpk_lg_i32 s96, 0x100
	s_cbranch_scc1 .Lsw_orig
	v_readlane_b32 s52, v254, 59
	v_lshrrev_b32_e32 v8, 8, v194
	v_and_b32_e32 v0, 63, v194
	v_lshlrev_b32_e32 v5, 1, v194
	v_readfirstlane_b32 s10, v8
	s_lshr_b32 s8, s22, 4
	s_and_b32 s9, s22, 15
	s_lshl_b32 s11, s22, 10
	s_add_u32 s54, s94, 0x48641000
	s_addc_u32 s55, s95, 0
	s_add_u32 s54, s54, s11
	s_addc_u32 s55, s55, 0
	s_cmp_lg_u32 s10, 0
	s_cbranch_scc1 .Lsw_pathb
	v_lshrrev_b32_e32 v1, 4, v194
	v_and_b32_e32 v2, 15, v194
	v_sub_u32_e32 v8, s8, v1
	v_max_i32_e32 v8, 0, v8
	v_subrev_u32_e32 v9, s8, v1
	v_max_i32_e32 v9, 0, v9
	s_lshl_b32 s11, s9, 4
	v_lshl_add_u32 v3, v8, 8, v2
	v_add_u32_e32 v3, s11, v3
	v_lshlrev_b32_e32 v3, 2, v3
	v_lshl_add_u32 v4, v9, 8, v2
	v_add_u32_e32 v4, s11, v4
	v_add_u32_e32 v4, 0x1000, v4
	v_lshlrev_b32_e32 v4, 2, v4
	v_cmp_ge_i32_e64 s[40:41], s8, v1
	v_cmp_le_i32_e64 s[42:43], s8, v1
	v_cmp_eq_u32_e64 s[44:45], s8, v1
	v_cmp_eq_u32_e64 s[46:47], s9, v2
	s_and_b64 s[44:45], s[44:45], s[46:47]
	s_add_u32 s48, s94, 0x4cec1000
	s_addc_u32 s49, s95, 0
	v_readlane_b32 s50, v254, 24
	v_readlane_b32 s51, v254, 25
	s_lshl_b32 s11, s52, 9
	s_add_i32 s11, s11, s9
	s_lshl_b32 s11, s11, 2
	s_add_u32 s50, s50, s11
	s_addc_u32 s51, s51, 0
	global_load_dword v32, v3, s[48:49]
	global_load_dword v48, v4, s[48:49]
	global_load_dword v64, v183, s[50:51] offset:0
	s_add_u32 s48, s48, 0x8000
	s_addc_u32 s49, s49, 0
	global_load_dword v33, v3, s[48:49]
	global_load_dword v49, v4, s[48:49]
	global_load_dword v65, v183, s[50:51] offset:64
	s_add_u32 s48, s48, 0x8000
	s_addc_u32 s49, s49, 0
	global_load_dword v34, v3, s[48:49]
	global_load_dword v50, v4, s[48:49]
	global_load_dword v66, v183, s[50:51] offset:128
	s_add_u32 s48, s48, 0x8000
	s_addc_u32 s49, s49, 0
	global_load_dword v35, v3, s[48:49]
	global_load_dword v51, v4, s[48:49]
	global_load_dword v67, v183, s[50:51] offset:192
	s_add_u32 s48, s48, 0x8000
	s_addc_u32 s49, s49, 0
	global_load_dword v36, v3, s[48:49]
	global_load_dword v52, v4, s[48:49]
	global_load_dword v68, v183, s[50:51] offset:256
	s_add_u32 s48, s48, 0x8000
	s_addc_u32 s49, s49, 0
	global_load_dword v37, v3, s[48:49]
	global_load_dword v53, v4, s[48:49]
	global_load_dword v69, v183, s[50:51] offset:320
	s_add_u32 s48, s48, 0x8000
	s_addc_u32 s49, s49, 0
	global_load_dword v38, v3, s[48:49]
	global_load_dword v54, v4, s[48:49]
	global_load_dword v70, v183, s[50:51] offset:384
	s_add_u32 s48, s48, 0x8000
	s_addc_u32 s49, s49, 0
	global_load_dword v39, v3, s[48:49]
	global_load_dword v55, v4, s[48:49]
	global_load_dword v71, v183, s[50:51] offset:448
	s_add_u32 s48, s48, 0x8000
	s_addc_u32 s49, s49, 0
	global_load_dword v40, v3, s[48:49]
	global_load_dword v56, v4, s[48:49]
	global_load_dword v72, v183, s[50:51] offset:512
	s_add_u32 s48, s48, 0x8000
	s_addc_u32 s49, s49, 0
	global_load_dword v41, v3, s[48:49]
	global_load_dword v57, v4, s[48:49]
	global_load_dword v73, v183, s[50:51] offset:576
	s_add_u32 s48, s48, 0x8000
	s_addc_u32 s49, s49, 0
	global_load_dword v42, v3, s[48:49]
	global_load_dword v58, v4, s[48:49]
	global_load_dword v74, v183, s[50:51] offset:640
	s_add_u32 s48, s48, 0x8000
	s_addc_u32 s49, s49, 0
	global_load_dword v43, v3, s[48:49]
	global_load_dword v59, v4, s[48:49]
	global_load_dword v75, v183, s[50:51] offset:704
	s_add_u32 s48, s48, 0x8000
	s_addc_u32 s49, s49, 0
	global_load_dword v44, v3, s[48:49]
	global_load_dword v60, v4, s[48:49]
	global_load_dword v76, v183, s[50:51] offset:768
	s_add_u32 s48, s48, 0x8000
	s_addc_u32 s49, s49, 0
	global_load_dword v45, v3, s[48:49]
	global_load_dword v61, v4, s[48:49]
	global_load_dword v77, v183, s[50:51] offset:832
	s_add_u32 s48, s48, 0x8000
	s_addc_u32 s49, s49, 0
	global_load_dword v46, v3, s[48:49]
	global_load_dword v62, v4, s[48:49]
	global_load_dword v78, v183, s[50:51] offset:896
	s_add_u32 s48, s48, 0x8000
	s_addc_u32 s49, s49, 0
	global_load_dword v47, v3, s[48:49]
	global_load_dword v63, v4, s[48:49]
	global_load_dword v79, v183, s[50:51] offset:960
	s_add_u32 s48, s48, 0x8000
	s_addc_u32 s49, s49, 0
	s_waitcnt vmcnt(0)
	v_cndmask_b32_e64 v32, 0, v32, s[40:41]
	v_cndmask_b32_e64 v48, 0, v48, s[42:43]
	v_cndmask_b32_e64 v64, 0, v64, s[44:45]
	v_add_f32_e32 v32, v32, v48
	v_add_f32_e32 v32, v32, v64
	v_cvt_pk_bf16_f32 v32, v32, v183
	global_store_short v5, v32, s[54:55]
	s_add_u32 s54, s54, 0x40000
	s_addc_u32 s55, s55, 0
	v_cndmask_b32_e64 v33, 0, v33, s[40:41]
	v_cndmask_b32_e64 v49, 0, v49, s[42:43]
	v_cndmask_b32_e64 v65, 0, v65, s[44:45]
	v_add_f32_e32 v33, v33, v49
	v_add_f32_e32 v33, v33, v65
	v_cvt_pk_bf16_f32 v33, v33, v183
	global_store_short v5, v33, s[54:55]
	s_add_u32 s54, s54, 0x40000
	s_addc_u32 s55, s55, 0
	v_cndmask_b32_e64 v34, 0, v34, s[40:41]
	v_cndmask_b32_e64 v50, 0, v50, s[42:43]
	v_cndmask_b32_e64 v66, 0, v66, s[44:45]
	v_add_f32_e32 v34, v34, v50
	v_add_f32_e32 v34, v34, v66
	v_cvt_pk_bf16_f32 v34, v34, v183
	global_store_short v5, v34, s[54:55]
	s_add_u32 s54, s54, 0x40000
	s_addc_u32 s55, s55, 0
	v_cndmask_b32_e64 v35, 0, v35, s[40:41]
	v_cndmask_b32_e64 v51, 0, v51, s[42:43]
	v_cndmask_b32_e64 v67, 0, v67, s[44:45]
	v_add_f32_e32 v35, v35, v51
	v_add_f32_e32 v35, v35, v67
	v_cvt_pk_bf16_f32 v35, v35, v183
	global_store_short v5, v35, s[54:55]
	s_add_u32 s54, s54, 0x40000
	s_addc_u32 s55, s55, 0
	v_cndmask_b32_e64 v36, 0, v36, s[40:41]
	v_cndmask_b32_e64 v52, 0, v52, s[42:43]
	v_cndmask_b32_e64 v68, 0, v68, s[44:45]
	v_add_f32_e32 v36, v36, v52
	v_add_f32_e32 v36, v36, v68
	v_cvt_pk_bf16_f32 v36, v36, v183
	global_store_short v5, v36, s[54:55]
	s_add_u32 s54, s54, 0x40000
	s_addc_u32 s55, s55, 0
	v_cndmask_b32_e64 v37, 0, v37, s[40:41]
; __device__ __forceinline__ bf16_t f2bf(float f) { return (bf16_t)(cvt_pk_bf16(f, 0.f) & 0xffffu); }
; __device__ __forceinline__ void s5_assemble_w(const int TID, const int BID, const Params& p, int l) {
;     ...
;         if (k < 256) { const int s = k >> 4, cp = k & 15; val = 0.f;
;             const int jf = s <= t ? t - s : 0, jb = s >= t ? s - t : 0;
;             const float kf = kmat[((((size_t)g * 2 + 0) * 16 + jf) * 16 + c) * 16 + cp], kb = kmat[((((size_t)g * 2 + 1) * 16 + jb) * 16 + c) * 16 + cp], dsk = p.in[12][l * 512 + g * 16 + c];
;             val = (s <= t ? kf : 0.f) + (s >= t ? kb : 0.f) + ((s == t && c == cp) ? dsk : 0.f);
;         } else { const int kk = k - 256, d = kk >> 7, ri = (kk >> 6) & 1, n = kk & 63, j = d == 0 ? t + 1 : 16 - t;
;             const float cr = cre[(((size_t)(l * 2 + d) * 32 + g) * 16 + c) * 64 + n], ci = cim[(((size_t)(l * 2 + d) * 32 + g) * 16 + c) * 64 + n];
;             const f32x2 pv = pw[((size_t)(g * 2 + d) * 17 + j) * 64 + n];
;             val = ri == 0 ? cr * pv.x - ci * pv.y : -(cr * pv.y + ci * pv.x); }
;         wmat[idx] = f2bf(val);
	v_cndmask_b32_e64 v53, 0, v53, s[42:43]
	v_cndmask_b32_e64 v69, 0, v69, s[44:45]
	v_add_f32_e32 v37, v37, v53
	v_add_f32_e32 v37, v37, v69
	v_cvt_pk_bf16_f32 v37, v37, v183
	global_store_short v5, v37, s[54:55]
	s_add_u32 s54, s54, 0x40000
	s_addc_u32 s55, s55, 0
	v_cndmask_b32_e64 v38, 0, v38, s[40:41]
	v_cndmask_b32_e64 v54, 0, v54, s[42:43]
	v_cndmask_b32_e64 v70, 0, v70, s[44:45]
	v_add_f32_e32 v38, v38, v54
	v_add_f32_e32 v38, v38, v70
	v_cvt_pk_bf16_f32 v38, v38, v183
	global_store_short v5, v38, s[54:55]
	s_add_u32 s54, s54, 0x40000
	s_addc_u32 s55, s55, 0
	v_cndmask_b32_e64 v39, 0, v39, s[40:41]
	v_cndmask_b32_e64 v55, 0, v55, s[42:43]
	v_cndmask_b32_e64 v71, 0, v71, s[44:45]
	v_add_f32_e32 v39, v39, v55
	v_add_f32_e32 v39, v39, v71
	v_cvt_pk_bf16_f32 v39, v39, v183
	global_store_short v5, v39, s[54:55]
	s_add_u32 s54, s54, 0x40000
	s_addc_u32 s55, s55, 0
	v_cndmask_b32_e64 v40, 0, v40, s[40:41]
	v_cndmask_b32_e64 v56, 0, v56, s[42:43]
	v_cndmask_b32_e64 v72, 0, v72, s[44:45]
	v_add_f32_e32 v40, v40, v56
	v_add_f32_e32 v40, v40, v72
	v_cvt_pk_bf16_f32 v40, v40, v183
	global_store_short v5, v40, s[54:55]
	s_add_u32 s54, s54, 0x40000
	s_addc_u32 s55, s55, 0
	v_cndmask_b32_e64 v41, 0, v41, s[40:41]
	v_cndmask_b32_e64 v57, 0, v57, s[42:43]
	v_cndmask_b32_e64 v73, 0, v73, s[44:45]
	v_add_f32_e32 v41, v41, v57
	v_add_f32_e32 v41, v41, v73
	v_cvt_pk_bf16_f32 v41, v41, v183
	global_store_short v5, v41, s[54:55]
	s_add_u32 s54, s54, 0x40000
	s_addc_u32 s55, s55, 0
	v_cndmask_b32_e64 v42, 0, v42, s[40:41]
	v_cndmask_b32_e64 v58, 0, v58, s[42:43]
	v_cndmask_b32_e64 v74, 0, v74, s[44:45]
	v_add_f32_e32 v42, v42, v58
	v_add_f32_e32 v42, v42, v74
	v_cvt_pk_bf16_f32 v42, v42, v183
	global_store_short v5, v42, s[54:55]
	s_add_u32 s54, s54, 0x40000
	s_addc_u32 s55, s55, 0
	v_cndmask_b32_e64 v43, 0, v43, s[40:41]
	v_cndmask_b32_e64 v59, 0, v59, s[42:43]
	v_cndmask_b32_e64 v75, 0, v75, s[44:45]
	v_add_f32_e32 v43, v43, v59
	v_add_f32_e32 v43, v43, v75
	v_cvt_pk_bf16_f32 v43, v43, v183
	global_store_short v5, v43, s[54:55]
	s_add_u32 s54, s54, 0x40000
	s_addc_u32 s55, s55, 0
	v_cndmask_b32_e64 v44, 0, v44, s[40:41]
	v_cndmask_b32_e64 v60, 0, v60, s[42:43]
	v_cndmask_b32_e64 v76, 0, v76, s[44:45]
	v_add_f32_e32 v44, v44, v60
	v_add_f32_e32 v44, v44, v76
	v_cvt_pk_bf16_f32 v44, v44, v183
	global_store_short v5, v44, s[54:55]
	s_add_u32 s54, s54, 0x40000
	s_addc_u32 s55, s55, 0
	v_cndmask_b32_e64 v45, 0, v45, s[40:41]
	v_cndmask_b32_e64 v61, 0, v61, s[42:43]
	v_cndmask_b32_e64 v77, 0, v77, s[44:45]
	v_add_f32_e32 v45, v45, v61
	v_add_f32_e32 v45, v45, v77
	v_cvt_pk_bf16_f32 v45, v45, v183
	global_store_short v5, v45, s[54:55]
	s_add_u32 s54, s54, 0x40000
	s_addc_u32 s55, s55, 0
	v_cndmask_b32_e64 v46, 0, v46, s[40:41]
	v_cndmask_b32_e64 v62, 0, v62, s[42:43]
	v_cndmask_b32_e64 v78, 0, v78, s[44:45]
	v_add_f32_e32 v46, v46, v62
	v_add_f32_e32 v46, v46, v78
	v_cvt_pk_bf16_f32 v46, v46, v183
	global_store_short v5, v46, s[54:55]
	s_add_u32 s54, s54, 0x40000
	s_addc_u32 s55, s55, 0
	v_cndmask_b32_e64 v47, 0, v47, s[40:41]
	v_cndmask_b32_e64 v63, 0, v63, s[42:43]
	v_cndmask_b32_e64 v79, 0, v79, s[44:45]
	v_add_f32_e32 v47, v47, v63
	v_add_f32_e32 v47, v47, v79
	v_cvt_pk_bf16_f32 v47, v47, v183
	global_store_short v5, v47, s[54:55]
	s_add_u32 s54, s54, 0x40000
	s_addc_u32 s55, s55, 0
	global_load_dword v32, v3, s[48:49]
	global_load_dword v48, v4, s[48:49]
	global_load_dword v64, v183, s[50:51] offset:1024
	s_add_u32 s48, s48, 0x8000
	s_addc_u32 s49, s49, 0
	global_load_dword v33, v3, s[48:49]
	global_load_dword v49, v4, s[48:49]
	global_load_dword v65, v183, s[50:51] offset:1088
	s_add_u32 s48, s48, 0x8000
	s_addc_u32 s49, s49, 0
	global_load_dword v34, v3, s[48:49]
	global_load_dword v50, v4, s[48:49]
	global_load_dword v66, v183, s[50:51] offset:1152
	s_add_u32 s48, s48, 0x8000
	s_addc_u32 s49, s49, 0
	global_load_dword v35, v3, s[48:49]
	global_load_dword v51, v4, s[48:49]
	global_load_dword v67, v183, s[50:51] offset:1216
	s_add_u32 s48, s48, 0x8000
	s_addc_u32 s49, s49, 0
	global_load_dword v36, v3, s[48:49]
	global_load_dword v52, v4, s[48:49]
	global_load_dword v68, v183, s[50:51] offset:1280
	s_add_u32 s48, s48, 0x8000
	s_addc_u32 s49, s49, 0
	global_load_dword v37, v3, s[48:49]
	global_load_dword v53, v4, s[48:49]
	global_load_dword v69, v183, s[50:51] offset:1344
	s_add_u32 s48, s48, 0x8000
	s_addc_u32 s49, s49, 0
	global_load_dword v38, v3, s[48:49]
	global_load_dword v54, v4, s[48:49]
	global_load_dword v70, v183, s[50:51] offset:1408
	s_add_u32 s48, s48, 0x8000
	s_addc_u32 s49, s49, 0
	global_load_dword v39, v3, s[48:49]
	global_load_dword v55, v4, s[48:49]
	global_load_dword v71, v183, s[50:51] offset:1472
	s_add_u32 s48, s48, 0x8000
	s_addc_u32 s49, s49, 0
	global_load_dword v40, v3, s[48:49]
	global_load_dword v56, v4, s[48:49]
	global_load_dword v72, v183, s[50:51] offset:1536
	s_add_u32 s48, s48, 0x8000
	s_addc_u32 s49, s49, 0
	global_load_dword v41, v3, s[48:49]
	global_load_dword v57, v4, s[48:49]
	global_load_dword v73, v183, s[50:51] offset:1600
	s_add_u32 s48, s48, 0x8000
	s_addc_u32 s49, s49, 0
	global_load_dword v42, v3, s[48:49]
	global_load_dword v58, v4, s[48:49]
	global_load_dword v74, v183, s[50:51] offset:1664
	s_add_u32 s48, s48, 0x8000
	s_addc_u32 s49, s49, 0
	global_load_dword v43, v3, s[48:49]
	global_load_dword v59, v4, s[48:49]
	global_load_dword v75, v183, s[50:51] offset:1728
	s_add_u32 s48, s48, 0x8000
	s_addc_u32 s49, s49, 0
	global_load_dword v44, v3, s[48:49]
	global_load_dword v60, v4, s[48:49]
	global_load_dword v76, v183, s[50:51] offset:1792
	s_add_u32 s48, s48, 0x8000
	s_addc_u32 s49, s49, 0
	global_load_dword v45, v3, s[48:49]
	global_load_dword v61, v4, s[48:49]
	global_load_dword v77, v183, s[50:51] offset:1856
	s_add_u32 s48, s48, 0x8000
	s_addc_u32 s49, s49, 0
	global_load_dword v46, v3, s[48:49]
	global_load_dword v62, v4, s[48:49]
	global_load_dword v78, v183, s[50:51] offset:1920
	s_add_u32 s48, s48, 0x8000
	s_addc_u32 s49, s49, 0
	global_load_dword v47, v3, s[48:49]
	global_load_dword v63, v4, s[48:49]
	global_load_dword v79, v183, s[50:51] offset:1984
	s_add_u32 s48, s48, 0x8000
	s_addc_u32 s49, s49, 0
	s_waitcnt vmcnt(0)
; __device__ __forceinline__ bf16_t f2bf(float f) { return (bf16_t)(cvt_pk_bf16(f, 0.f) & 0xffffu); }
; __device__ __forceinline__ void s5_assemble_w(const int TID, const int BID, const Params& p, int l) {
;     ...
;         if (k < 256) { const int s = k >> 4, cp = k & 15; val = 0.f;
;             const int jf = s <= t ? t - s : 0, jb = s >= t ? s - t : 0;
;             const float kf = kmat[((((size_t)g * 2 + 0) * 16 + jf) * 16 + c) * 16 + cp], kb = kmat[((((size_t)g * 2 + 1) * 16 + jb) * 16 + c) * 16 + cp], dsk = p.in[12][l * 512 + g * 16 + c];
;             val = (s <= t ? kf : 0.f) + (s >= t ? kb : 0.f) + ((s == t && c == cp) ? dsk : 0.f);
;         } else { const int kk = k - 256, d = kk >> 7, ri = (kk >> 6) & 1, n = kk & 63, j = d == 0 ? t + 1 : 16 - t;
;             const float cr = cre[(((size_t)(l * 2 + d) * 32 + g) * 16 + c) * 64 + n], ci = cim[(((size_t)(l * 2 + d) * 32 + g) * 16 + c) * 64 + n];
;             const f32x2 pv = pw[((size_t)(g * 2 + d) * 17 + j) * 64 + n];
;             val = ri == 0 ? cr * pv.x - ci * pv.y : -(cr * pv.y + ci * pv.x); }
;         wmat[idx] = f2bf(val);
	v_cndmask_b32_e64 v32, 0, v32, s[40:41]
	v_cndmask_b32_e64 v48, 0, v48, s[42:43]
	v_cndmask_b32_e64 v64, 0, v64, s[44:45]
	v_add_f32_e32 v32, v32, v48
	v_add_f32_e32 v32, v32, v64
	v_cvt_pk_bf16_f32 v32, v32, v183
	global_store_short v5, v32, s[54:55]
	s_add_u32 s54, s54, 0x40000
	s_addc_u32 s55, s55, 0
	v_cndmask_b32_e64 v33, 0, v33, s[40:41]
	v_cndmask_b32_e64 v49, 0, v49, s[42:43]
	v_cndmask_b32_e64 v65, 0, v65, s[44:45]
	v_add_f32_e32 v33, v33, v49
	v_add_f32_e32 v33, v33, v65
	v_cvt_pk_bf16_f32 v33, v33, v183
	global_store_short v5, v33, s[54:55]
	s_add_u32 s54, s54, 0x40000
	s_addc_u32 s55, s55, 0
	v_cndmask_b32_e64 v34, 0, v34, s[40:41]
	v_cndmask_b32_e64 v50, 0, v50, s[42:43]
	v_cndmask_b32_e64 v66, 0, v66, s[44:45]
	v_add_f32_e32 v34, v34, v50
	v_add_f32_e32 v34, v34, v66
	v_cvt_pk_bf16_f32 v34, v34, v183
	global_store_short v5, v34, s[54:55]
	s_add_u32 s54, s54, 0x40000
	s_addc_u32 s55, s55, 0
	v_cndmask_b32_e64 v35, 0, v35, s[40:41]
	v_cndmask_b32_e64 v51, 0, v51, s[42:43]
	v_cndmask_b32_e64 v67, 0, v67, s[44:45]
	v_add_f32_e32 v35, v35, v51
	v_add_f32_e32 v35, v35, v67
	v_cvt_pk_bf16_f32 v35, v35, v183
	global_store_short v5, v35, s[54:55]
	s_add_u32 s54, s54, 0x40000
	s_addc_u32 s55, s55, 0
	v_cndmask_b32_e64 v36, 0, v36, s[40:41]
	v_cndmask_b32_e64 v52, 0, v52, s[42:43]
	v_cndmask_b32_e64 v68, 0, v68, s[44:45]
	v_add_f32_e32 v36, v36, v52
	v_add_f32_e32 v36, v36, v68
	v_cvt_pk_bf16_f32 v36, v36, v183
	global_store_short v5, v36, s[54:55]
	s_add_u32 s54, s54, 0x40000
	s_addc_u32 s55, s55, 0
	v_cndmask_b32_e64 v37, 0, v37, s[40:41]
	v_cndmask_b32_e64 v53, 0, v53, s[42:43]
	v_cndmask_b32_e64 v69, 0, v69, s[44:45]
	v_add_f32_e32 v37, v37, v53
	v_add_f32_e32 v37, v37, v69
	v_cvt_pk_bf16_f32 v37, v37, v183
	global_store_short v5, v37, s[54:55]
	s_add_u32 s54, s54, 0x40000
	s_addc_u32 s55, s55, 0
	v_cndmask_b32_e64 v38, 0, v38, s[40:41]
	v_cndmask_b32_e64 v54, 0, v54, s[42:43]
	v_cndmask_b32_e64 v70, 0, v70, s[44:45]
	v_add_f32_e32 v38, v38, v54
	v_add_f32_e32 v38, v38, v70
	v_cvt_pk_bf16_f32 v38, v38, v183
	global_store_short v5, v38, s[54:55]
	s_add_u32 s54, s54, 0x40000
	s_addc_u32 s55, s55, 0
	v_cndmask_b32_e64 v39, 0, v39, s[40:41]
	v_cndmask_b32_e64 v55, 0, v55, s[42:43]
	v_cndmask_b32_e64 v71, 0, v71, s[44:45]
	v_add_f32_e32 v39, v39, v55
	v_add_f32_e32 v39, v39, v71
	v_cvt_pk_bf16_f32 v39, v39, v183
	global_store_short v5, v39, s[54:55]
	s_add_u32 s54, s54, 0x40000
	s_addc_u32 s55, s55, 0
	v_cndmask_b32_e64 v40, 0, v40, s[40:41]
	v_cndmask_b32_e64 v56, 0, v56, s[42:43]
	v_cndmask_b32_e64 v72, 0, v72, s[44:45]
	v_add_f32_e32 v40, v40, v56
	v_add_f32_e32 v40, v40, v72
	v_cvt_pk_bf16_f32 v40, v40, v183
	global_store_short v5, v40, s[54:55]
	s_add_u32 s54, s54, 0x40000
	s_addc_u32 s55, s55, 0
	v_cndmask_b32_e64 v41, 0, v41, s[40:41]
	v_cndmask_b32_e64 v57, 0, v57, s[42:43]
	v_cndmask_b32_e64 v73, 0, v73, s[44:45]
	v_add_f32_e32 v41, v41, v57
	v_add_f32_e32 v41, v41, v73
	v_cvt_pk_bf16_f32 v41, v41, v183
	global_store_short v5, v41, s[54:55]
	s_add_u32 s54, s54, 0x40000
	s_addc_u32 s55, s55, 0
	v_cndmask_b32_e64 v42, 0, v42, s[40:41]
	v_cndmask_b32_e64 v58, 0, v58, s[42:43]
	v_cndmask_b32_e64 v74, 0, v74, s[44:45]
	v_add_f32_e32 v42, v42, v58
	v_add_f32_e32 v42, v42, v74
	v_cvt_pk_bf16_f32 v42, v42, v183
	global_store_short v5, v42, s[54:55]
	s_add_u32 s54, s54, 0x40000
	s_addc_u32 s55, s55, 0
	v_cndmask_b32_e64 v43, 0, v43, s[40:41]
	v_cndmask_b32_e64 v59, 0, v59, s[42:43]
	v_cndmask_b32_e64 v75, 0, v75, s[44:45]
	v_add_f32_e32 v43, v43, v59
	v_add_f32_e32 v43, v43, v75
	v_cvt_pk_bf16_f32 v43, v43, v183
	global_store_short v5, v43, s[54:55]
	s_add_u32 s54, s54, 0x40000
	s_addc_u32 s55, s55, 0
	v_cndmask_b32_e64 v44, 0, v44, s[40:41]
	v_cndmask_b32_e64 v60, 0, v60, s[42:43]
	v_cndmask_b32_e64 v76, 0, v76, s[44:45]
	v_add_f32_e32 v44, v44, v60
	v_add_f32_e32 v44, v44, v76
	v_cvt_pk_bf16_f32 v44, v44, v183
	global_store_short v5, v44, s[54:55]
	s_add_u32 s54, s54, 0x40000
	s_addc_u32 s55, s55, 0
	v_cndmask_b32_e64 v45, 0, v45, s[40:41]
	v_cndmask_b32_e64 v61, 0, v61, s[42:43]
	v_cndmask_b32_e64 v77, 0, v77, s[44:45]
	v_add_f32_e32 v45, v45, v61
	v_add_f32_e32 v45, v45, v77
	v_cvt_pk_bf16_f32 v45, v45, v183
	global_store_short v5, v45, s[54:55]
	s_add_u32 s54, s54, 0x40000
	s_addc_u32 s55, s55, 0
	v_cndmask_b32_e64 v46, 0, v46, s[40:41]
	v_cndmask_b32_e64 v62, 0, v62, s[42:43]
	v_cndmask_b32_e64 v78, 0, v78, s[44:45]
	v_add_f32_e32 v46, v46, v62
	v_add_f32_e32 v46, v46, v78
	v_cvt_pk_bf16_f32 v46, v46, v183
	global_store_short v5, v46, s[54:55]
	s_add_u32 s54, s54, 0x40000
	s_addc_u32 s55, s55, 0
	v_cndmask_b32_e64 v47, 0, v47, s[40:41]
	v_cndmask_b32_e64 v63, 0, v63, s[42:43]
	v_cndmask_b32_e64 v79, 0, v79, s[44:45]
	v_add_f32_e32 v47, v47, v63
	v_add_f32_e32 v47, v47, v79
	v_cvt_pk_bf16_f32 v47, v47, v183
	global_store_short v5, v47, s[54:55]
	s_add_u32 s54, s54, 0x40000
	s_addc_u32 s55, s55, 0
	s_branch .LBB0_1022
; __device__ __forceinline__ bf16_t f2bf(float f) { return (bf16_t)(cvt_pk_bf16(f, 0.f) & 0xffffu); }
; __device__ __forceinline__ void s5_assemble_w(const int TID, const int BID, const Params& p, int l) {
;     ...
;         } else { const int kk = k - 256, d = kk >> 7, ri = (kk >> 6) & 1, n = kk & 63, j = d == 0 ? t + 1 : 16 - t;
;             const float cr = cre[(((size_t)(l * 2 + d) * 32 + g) * 16 + c) * 64 + n], ci = cim[(((size_t)(l * 2 + d) * 32 + g) * 16 + c) * 64 + n];
;             const f32x2 pv = pw[((size_t)(g * 2 + d) * 17 + j) * 64 + n];
;             val = ri == 0 ? cr * pv.x - ci * pv.y : -(cr * pv.y + ci * pv.x); }
;         wmat[idx] = f2bf(val);
.Lsw_pathb:
	s_lshr_b32 s11, s10, 0
	v_lshrrev_b32_e32 v8, 6, v194
	v_lshlrev_b32_e32 v6, 2, v0
	v_lshlrev_b32_e32 v7, 3, v0
	v_readfirstlane_b32 s23, v8
	s_sub_i32 s23, s23, 4
	s_lshr_b32 s24, s23, 1
	s_and_b32 s23, s23, 1
	s_add_i32 s10, s8, 1
	s_sub_i32 s11, 16, s8
	s_cmp_eq_u32 s24, 0
	s_cselect_b32 s10, s10, s11
	s_mul_i32 s11, s24, 17
	s_add_i32 s10, s10, s11
	s_lshl_b32 s10, s10, 9
	s_add_u32 s60, s94, 0x48221000
	s_addc_u32 s61, s95, 0
	s_add_u32 s60, s60, s88
	s_addc_u32 s61, s61, s89
	s_add_u32 s60, s60, s10
	s_addc_u32 s61, s61, 0
	s_lshl_b32 s10, s52, 1
	s_add_i32 s10, s10, s24
	s_lshl_b32 s10, s10, 17
	s_lshl_b32 s11, s9, 8
	s_add_i32 s10, s10, s11
	v_readlane_b32 s56, v254, 20
	v_readlane_b32 s57, v254, 21
	v_readlane_b32 s58, v254, 22
	v_readlane_b32 s59, v254, 23
	s_add_u32 s56, s56, s10
	s_addc_u32 s57, s57, 0
	s_add_u32 s58, s58, s10
	s_addc_u32 s59, s59, 0
	s_cmp_lg_u32 s23, 0
	s_cselect_b64 s[46:47], -1, 0
	s_cselect_b32 s62, 0x80000000, 0
	global_load_dword v32, v6, s[56:57]
	global_load_dword v48, v6, s[58:59]
	global_load_dwordx2 v[64:65], v7, s[60:61]
	s_add_u32 s56, s56, 0x1000
	s_addc_u32 s57, s57, 0
	s_add_u32 s58, s58, 0x1000
	s_addc_u32 s59, s59, 0
	s_add_u32 s60, s60, 0x4400
	s_addc_u32 s61, s61, 0
	global_load_dword v33, v6, s[56:57]
	global_load_dword v49, v6, s[58:59]
	global_load_dwordx2 v[66:67], v7, s[60:61]
	s_add_u32 s56, s56, 0x1000
	s_addc_u32 s57, s57, 0
	s_add_u32 s58, s58, 0x1000
	s_addc_u32 s59, s59, 0
	s_add_u32 s60, s60, 0x4400
	s_addc_u32 s61, s61, 0
	global_load_dword v34, v6, s[56:57]
	global_load_dword v50, v6, s[58:59]
	global_load_dwordx2 v[68:69], v7, s[60:61]
	s_add_u32 s56, s56, 0x1000
	s_addc_u32 s57, s57, 0
	s_add_u32 s58, s58, 0x1000
	s_addc_u32 s59, s59, 0
	s_add_u32 s60, s60, 0x4400
	s_addc_u32 s61, s61, 0
	global_load_dword v35, v6, s[56:57]
	global_load_dword v51, v6, s[58:59]
	global_load_dwordx2 v[70:71], v7, s[60:61]
	s_add_u32 s56, s56, 0x1000
	s_addc_u32 s57, s57, 0
	s_add_u32 s58, s58, 0x1000
	s_addc_u32 s59, s59, 0
	s_add_u32 s60, s60, 0x4400
	s_addc_u32 s61, s61, 0
	global_load_dword v36, v6, s[56:57]
	global_load_dword v52, v6, s[58:59]
	global_load_dwordx2 v[72:73], v7, s[60:61]
	s_add_u32 s56, s56, 0x1000
	s_addc_u32 s57, s57, 0
	s_add_u32 s58, s58, 0x1000
	s_addc_u32 s59, s59, 0
	s_add_u32 s60, s60, 0x4400
	s_addc_u32 s61, s61, 0
	global_load_dword v37, v6, s[56:57]
	global_load_dword v53, v6, s[58:59]
	global_load_dwordx2 v[74:75], v7, s[60:61]
	s_add_u32 s56, s56, 0x1000
	s_addc_u32 s57, s57, 0
	s_add_u32 s58, s58, 0x1000
	s_addc_u32 s59, s59, 0
	s_add_u32 s60, s60, 0x4400
	s_addc_u32 s61, s61, 0
	global_load_dword v38, v6, s[56:57]
	global_load_dword v54, v6, s[58:59]
	global_load_dwordx2 v[76:77], v7, s[60:61]
	s_add_u32 s56, s56, 0x1000
	s_addc_u32 s57, s57, 0
	s_add_u32 s58, s58, 0x1000
	s_addc_u32 s59, s59, 0
	s_add_u32 s60, s60, 0x4400
	s_addc_u32 s61, s61, 0
	global_load_dword v39, v6, s[56:57]
	global_load_dword v55, v6, s[58:59]
	global_load_dwordx2 v[78:79], v7, s[60:61]
	s_add_u32 s56, s56, 0x1000
	s_addc_u32 s57, s57, 0
	s_add_u32 s58, s58, 0x1000
	s_addc_u32 s59, s59, 0
	s_add_u32 s60, s60, 0x4400
	s_addc_u32 s61, s61, 0
	global_load_dword v40, v6, s[56:57]
	global_load_dword v56, v6, s[58:59]
	global_load_dwordx2 v[80:81], v7, s[60:61]
	s_add_u32 s56, s56, 0x1000
	s_addc_u32 s57, s57, 0
	s_add_u32 s58, s58, 0x1000
	s_addc_u32 s59, s59, 0
	s_add_u32 s60, s60, 0x4400
	s_addc_u32 s61, s61, 0
	global_load_dword v41, v6, s[56:57]
	global_load_dword v57, v6, s[58:59]
	global_load_dwordx2 v[82:83], v7, s[60:61]
	s_add_u32 s56, s56, 0x1000
	s_addc_u32 s57, s57, 0
	s_add_u32 s58, s58, 0x1000
	s_addc_u32 s59, s59, 0
	s_add_u32 s60, s60, 0x4400
	s_addc_u32 s61, s61, 0
	global_load_dword v42, v6, s[56:57]
	global_load_dword v58, v6, s[58:59]
	global_load_dwordx2 v[84:85], v7, s[60:61]
	s_add_u32 s56, s56, 0x1000
	s_addc_u32 s57, s57, 0
	s_add_u32 s58, s58, 0x1000
	s_addc_u32 s59, s59, 0
	s_add_u32 s60, s60, 0x4400
	s_addc_u32 s61, s61, 0
	global_load_dword v43, v6, s[56:57]
	global_load_dword v59, v6, s[58:59]
	global_load_dwordx2 v[86:87], v7, s[60:61]
	s_add_u32 s56, s56, 0x1000
	s_addc_u32 s57, s57, 0
	s_add_u32 s58, s58, 0x1000
	s_addc_u32 s59, s59, 0
	s_add_u32 s60, s60, 0x4400
	s_addc_u32 s61, s61, 0
	global_load_dword v44, v6, s[56:57]
	global_load_dword v60, v6, s[58:59]
	global_load_dwordx2 v[88:89], v7, s[60:61]
	s_add_u32 s56, s56, 0x1000
	s_addc_u32 s57, s57, 0
	s_add_u32 s58, s58, 0x1000
	s_addc_u32 s59, s59, 0
	s_add_u32 s60, s60, 0x4400
	s_addc_u32 s61, s61, 0
	global_load_dword v45, v6, s[56:57]
	global_load_dword v61, v6, s[58:59]
	global_load_dwordx2 v[90:91], v7, s[60:61]
	s_add_u32 s56, s56, 0x1000
	s_addc_u32 s57, s57, 0
	s_add_u32 s58, s58, 0x1000
	s_addc_u32 s59, s59, 0
	s_add_u32 s60, s60, 0x4400
	s_addc_u32 s61, s61, 0
	global_load_dword v46, v6, s[56:57]
	global_load_dword v62, v6, s[58:59]
	global_load_dwordx2 v[92:93], v7, s[60:61]
	s_add_u32 s56, s56, 0x1000
	s_addc_u32 s57, s57, 0
	s_add_u32 s58, s58, 0x1000
	s_addc_u32 s59, s59, 0
	s_add_u32 s60, s60, 0x4400
	s_addc_u32 s61, s61, 0
	global_load_dword v47, v6, s[56:57]
	global_load_dword v63, v6, s[58:59]
	global_load_dwordx2 v[94:95], v7, s[60:61]
	s_add_u32 s56, s56, 0x1000
	s_addc_u32 s57, s57, 0
	s_add_u32 s58, s58, 0x1000
	s_addc_u32 s59, s59, 0
	s_add_u32 s60, s60, 0x4400
	s_addc_u32 s61, s61, 0
	s_waitcnt vmcnt(0)
; __device__ __forceinline__ bf16_t f2bf(float f) { return (bf16_t)(cvt_pk_bf16(f, 0.f) & 0xffffu); }
; __device__ __forceinline__ void s5_assemble_w(const int TID, const int BID, const Params& p, int l) {
;     ...
;         } else { const int kk = k - 256, d = kk >> 7, ri = (kk >> 6) & 1, n = kk & 63, j = d == 0 ? t + 1 : 16 - t;
;             const float cr = cre[(((size_t)(l * 2 + d) * 32 + g) * 16 + c) * 64 + n], ci = cim[(((size_t)(l * 2 + d) * 32 + g) * 16 + c) * 64 + n];
;             const f32x2 pv = pw[((size_t)(g * 2 + d) * 17 + j) * 64 + n];
;             val = ri == 0 ? cr * pv.x - ci * pv.y : -(cr * pv.y + ci * pv.x); }
;         wmat[idx] = f2bf(val);
	v_cndmask_b32_e64 v8, v64, v65, s[46:47]
	v_cndmask_b32_e64 v9, v65, v64, s[46:47]
	v_mul_f32_e32 v8, v32, v8
	v_mul_f32_e32 v9, v48, v9
	v_xor_b32_e32 v8, s62, v8
	v_sub_f32_e32 v8, v8, v9
	v_cvt_pk_bf16_f32 v32, v8, v183
	global_store_short v5, v32, s[54:55]
	s_add_u32 s54, s54, 0x40000
	s_addc_u32 s55, s55, 0
	v_cndmask_b32_e64 v8, v66, v67, s[46:47]
	v_cndmask_b32_e64 v9, v67, v66, s[46:47]
	v_mul_f32_e32 v8, v33, v8
	v_mul_f32_e32 v9, v49, v9
	v_xor_b32_e32 v8, s62, v8
	v_sub_f32_e32 v8, v8, v9
	v_cvt_pk_bf16_f32 v33, v8, v183
	global_store_short v5, v33, s[54:55]
	s_add_u32 s54, s54, 0x40000
	s_addc_u32 s55, s55, 0
	v_cndmask_b32_e64 v8, v68, v69, s[46:47]
	v_cndmask_b32_e64 v9, v69, v68, s[46:47]
	v_mul_f32_e32 v8, v34, v8
	v_mul_f32_e32 v9, v50, v9
	v_xor_b32_e32 v8, s62, v8
	v_sub_f32_e32 v8, v8, v9
	v_cvt_pk_bf16_f32 v34, v8, v183
	global_store_short v5, v34, s[54:55]
	s_add_u32 s54, s54, 0x40000
	s_addc_u32 s55, s55, 0
	v_cndmask_b32_e64 v8, v70, v71, s[46:47]
	v_cndmask_b32_e64 v9, v71, v70, s[46:47]
	v_mul_f32_e32 v8, v35, v8
	v_mul_f32_e32 v9, v51, v9
	v_xor_b32_e32 v8, s62, v8
	v_sub_f32_e32 v8, v8, v9
	v_cvt_pk_bf16_f32 v35, v8, v183
	global_store_short v5, v35, s[54:55]
	s_add_u32 s54, s54, 0x40000
	s_addc_u32 s55, s55, 0
	v_cndmask_b32_e64 v8, v72, v73, s[46:47]
	v_cndmask_b32_e64 v9, v73, v72, s[46:47]
	v_mul_f32_e32 v8, v36, v8
	v_mul_f32_e32 v9, v52, v9
	v_xor_b32_e32 v8, s62, v8
	v_sub_f32_e32 v8, v8, v9
	v_cvt_pk_bf16_f32 v36, v8, v183
	global_store_short v5, v36, s[54:55]
	s_add_u32 s54, s54, 0x40000
	s_addc_u32 s55, s55, 0
	v_cndmask_b32_e64 v8, v74, v75, s[46:47]
	v_cndmask_b32_e64 v9, v75, v74, s[46:47]
	v_mul_f32_e32 v8, v37, v8
	v_mul_f32_e32 v9, v53, v9
	v_xor_b32_e32 v8, s62, v8
	v_sub_f32_e32 v8, v8, v9
	v_cvt_pk_bf16_f32 v37, v8, v183
	global_store_short v5, v37, s[54:55]
	s_add_u32 s54, s54, 0x40000
	s_addc_u32 s55, s55, 0
	v_cndmask_b32_e64 v8, v76, v77, s[46:47]
	v_cndmask_b32_e64 v9, v77, v76, s[46:47]
	v_mul_f32_e32 v8, v38, v8
	v_mul_f32_e32 v9, v54, v9
	v_xor_b32_e32 v8, s62, v8
	v_sub_f32_e32 v8, v8, v9
	v_cvt_pk_bf16_f32 v38, v8, v183
	global_store_short v5, v38, s[54:55]
	s_add_u32 s54, s54, 0x40000
	s_addc_u32 s55, s55, 0
	v_cndmask_b32_e64 v8, v78, v79, s[46:47]
	v_cndmask_b32_e64 v9, v79, v78, s[46:47]
	v_mul_f32_e32 v8, v39, v8
	v_mul_f32_e32 v9, v55, v9
	v_xor_b32_e32 v8, s62, v8
	v_sub_f32_e32 v8, v8, v9
	v_cvt_pk_bf16_f32 v39, v8, v183
	global_store_short v5, v39, s[54:55]
	s_add_u32 s54, s54, 0x40000
	s_addc_u32 s55, s55, 0
	v_cndmask_b32_e64 v8, v80, v81, s[46:47]
	v_cndmask_b32_e64 v9, v81, v80, s[46:47]
	v_mul_f32_e32 v8, v40, v8
	v_mul_f32_e32 v9, v56, v9
	v_xor_b32_e32 v8, s62, v8
	v_sub_f32_e32 v8, v8, v9
	v_cvt_pk_bf16_f32 v40, v8, v183
	global_store_short v5, v40, s[54:55]
	s_add_u32 s54, s54, 0x40000
	s_addc_u32 s55, s55, 0
	v_cndmask_b32_e64 v8, v82, v83, s[46:47]
	v_cndmask_b32_e64 v9, v83, v82, s[46:47]
	v_mul_f32_e32 v8, v41, v8
	v_mul_f32_e32 v9, v57, v9
	v_xor_b32_e32 v8, s62, v8
	v_sub_f32_e32 v8, v8, v9
	v_cvt_pk_bf16_f32 v41, v8, v183
	global_store_short v5, v41, s[54:55]
	s_add_u32 s54, s54, 0x40000
	s_addc_u32 s55, s55, 0
	v_cndmask_b32_e64 v8, v84, v85, s[46:47]
	v_cndmask_b32_e64 v9, v85, v84, s[46:47]
	v_mul_f32_e32 v8, v42, v8
	v_mul_f32_e32 v9, v58, v9
	v_xor_b32_e32 v8, s62, v8
	v_sub_f32_e32 v8, v8, v9
	v_cvt_pk_bf16_f32 v42, v8, v183
	global_store_short v5, v42, s[54:55]
	s_add_u32 s54, s54, 0x40000
	s_addc_u32 s55, s55, 0
	v_cndmask_b32_e64 v8, v86, v87, s[46:47]
	v_cndmask_b32_e64 v9, v87, v86, s[46:47]
	v_mul_f32_e32 v8, v43, v8
	v_mul_f32_e32 v9, v59, v9
	v_xor_b32_e32 v8, s62, v8
	v_sub_f32_e32 v8, v8, v9
	v_cvt_pk_bf16_f32 v43, v8, v183
	global_store_short v5, v43, s[54:55]
	s_add_u32 s54, s54, 0x40000
	s_addc_u32 s55, s55, 0
	v_cndmask_b32_e64 v8, v88, v89, s[46:47]
	v_cndmask_b32_e64 v9, v89, v88, s[46:47]
	v_mul_f32_e32 v8, v44, v8
	v_mul_f32_e32 v9, v60, v9
	v_xor_b32_e32 v8, s62, v8
	v_sub_f32_e32 v8, v8, v9
	v_cvt_pk_bf16_f32 v44, v8, v183
	global_store_short v5, v44, s[54:55]
	s_add_u32 s54, s54, 0x40000
	s_addc_u32 s55, s55, 0
	v_cndmask_b32_e64 v8, v90, v91, s[46:47]
	v_cndmask_b32_e64 v9, v91, v90, s[46:47]
	v_mul_f32_e32 v8, v45, v8
	v_mul_f32_e32 v9, v61, v9
	v_xor_b32_e32 v8, s62, v8
	v_sub_f32_e32 v8, v8, v9
	v_cvt_pk_bf16_f32 v45, v8, v183
	global_store_short v5, v45, s[54:55]
	s_add_u32 s54, s54, 0x40000
	s_addc_u32 s55, s55, 0
	v_cndmask_b32_e64 v8, v92, v93, s[46:47]
	v_cndmask_b32_e64 v9, v93, v92, s[46:47]
	v_mul_f32_e32 v8, v46, v8
	v_mul_f32_e32 v9, v62, v9
	v_xor_b32_e32 v8, s62, v8
	v_sub_f32_e32 v8, v8, v9
	v_cvt_pk_bf16_f32 v46, v8, v183
	global_store_short v5, v46, s[54:55]
	s_add_u32 s54, s54, 0x40000
	s_addc_u32 s55, s55, 0
	v_cndmask_b32_e64 v8, v94, v95, s[46:47]
	v_cndmask_b32_e64 v9, v95, v94, s[46:47]
	v_mul_f32_e32 v8, v47, v8
	v_mul_f32_e32 v9, v63, v9
	v_xor_b32_e32 v8, s62, v8
	v_sub_f32_e32 v8, v8, v9
	v_cvt_pk_bf16_f32 v47, v8, v183
	global_store_short v5, v47, s[54:55]
	s_add_u32 s54, s54, 0x40000
	s_addc_u32 s55, s55, 0
	global_load_dword v32, v6, s[56:57]
	global_load_dword v48, v6, s[58:59]
	global_load_dwordx2 v[64:65], v7, s[60:61]
	s_add_u32 s56, s56, 0x1000
	s_addc_u32 s57, s57, 0
	s_add_u32 s58, s58, 0x1000
	s_addc_u32 s59, s59, 0
	s_add_u32 s60, s60, 0x4400
	s_addc_u32 s61, s61, 0
	global_load_dword v33, v6, s[56:57]
	global_load_dword v49, v6, s[58:59]
	global_load_dwordx2 v[66:67], v7, s[60:61]
	s_add_u32 s56, s56, 0x1000
	s_addc_u32 s57, s57, 0
	s_add_u32 s58, s58, 0x1000
	s_addc_u32 s59, s59, 0
	s_add_u32 s60, s60, 0x4400
	s_addc_u32 s61, s61, 0
	global_load_dword v34, v6, s[56:57]
; __device__ __forceinline__ bf16_t f2bf(float f) { return (bf16_t)(cvt_pk_bf16(f, 0.f) & 0xffffu); }
; __device__ __forceinline__ void s5_assemble_w(const int TID, const int BID, const Params& p, int l) {
;     ...
;         } else { const int kk = k - 256, d = kk >> 7, ri = (kk >> 6) & 1, n = kk & 63, j = d == 0 ? t + 1 : 16 - t;
;             const float cr = cre[(((size_t)(l * 2 + d) * 32 + g) * 16 + c) * 64 + n], ci = cim[(((size_t)(l * 2 + d) * 32 + g) * 16 + c) * 64 + n];
;             const f32x2 pv = pw[((size_t)(g * 2 + d) * 17 + j) * 64 + n];
;             val = ri == 0 ? cr * pv.x - ci * pv.y : -(cr * pv.y + ci * pv.x); }
;         wmat[idx] = f2bf(val);
	global_load_dword v50, v6, s[58:59]
	global_load_dwordx2 v[68:69], v7, s[60:61]
	s_add_u32 s56, s56, 0x1000
	s_addc_u32 s57, s57, 0
	s_add_u32 s58, s58, 0x1000
	s_addc_u32 s59, s59, 0
	s_add_u32 s60, s60, 0x4400
	s_addc_u32 s61, s61, 0
	global_load_dword v35, v6, s[56:57]
	global_load_dword v51, v6, s[58:59]
	global_load_dwordx2 v[70:71], v7, s[60:61]
	s_add_u32 s56, s56, 0x1000
	s_addc_u32 s57, s57, 0
	s_add_u32 s58, s58, 0x1000
	s_addc_u32 s59, s59, 0
	s_add_u32 s60, s60, 0x4400
	s_addc_u32 s61, s61, 0
	global_load_dword v36, v6, s[56:57]
	global_load_dword v52, v6, s[58:59]
	global_load_dwordx2 v[72:73], v7, s[60:61]
	s_add_u32 s56, s56, 0x1000
	s_addc_u32 s57, s57, 0
	s_add_u32 s58, s58, 0x1000
	s_addc_u32 s59, s59, 0
	s_add_u32 s60, s60, 0x4400
	s_addc_u32 s61, s61, 0
	global_load_dword v37, v6, s[56:57]
	global_load_dword v53, v6, s[58:59]
	global_load_dwordx2 v[74:75], v7, s[60:61]
	s_add_u32 s56, s56, 0x1000
	s_addc_u32 s57, s57, 0
	s_add_u32 s58, s58, 0x1000
	s_addc_u32 s59, s59, 0
	s_add_u32 s60, s60, 0x4400
	s_addc_u32 s61, s61, 0
	global_load_dword v38, v6, s[56:57]
	global_load_dword v54, v6, s[58:59]
	global_load_dwordx2 v[76:77], v7, s[60:61]
	s_add_u32 s56, s56, 0x1000
	s_addc_u32 s57, s57, 0
	s_add_u32 s58, s58, 0x1000
	s_addc_u32 s59, s59, 0
	s_add_u32 s60, s60, 0x4400
	s_addc_u32 s61, s61, 0
	global_load_dword v39, v6, s[56:57]
	global_load_dword v55, v6, s[58:59]
	global_load_dwordx2 v[78:79], v7, s[60:61]
	s_add_u32 s56, s56, 0x1000
	s_addc_u32 s57, s57, 0
	s_add_u32 s58, s58, 0x1000
	s_addc_u32 s59, s59, 0
	s_add_u32 s60, s60, 0x4400
	s_addc_u32 s61, s61, 0
	global_load_dword v40, v6, s[56:57]
	global_load_dword v56, v6, s[58:59]
	global_load_dwordx2 v[80:81], v7, s[60:61]
	s_add_u32 s56, s56, 0x1000
	s_addc_u32 s57, s57, 0
	s_add_u32 s58, s58, 0x1000
	s_addc_u32 s59, s59, 0
	s_add_u32 s60, s60, 0x4400
	s_addc_u32 s61, s61, 0
	global_load_dword v41, v6, s[56:57]
	global_load_dword v57, v6, s[58:59]
	global_load_dwordx2 v[82:83], v7, s[60:61]
	s_add_u32 s56, s56, 0x1000
	s_addc_u32 s57, s57, 0
	s_add_u32 s58, s58, 0x1000
	s_addc_u32 s59, s59, 0
	s_add_u32 s60, s60, 0x4400
	s_addc_u32 s61, s61, 0
	global_load_dword v42, v6, s[56:57]
	global_load_dword v58, v6, s[58:59]
	global_load_dwordx2 v[84:85], v7, s[60:61]
	s_add_u32 s56, s56, 0x1000
	s_addc_u32 s57, s57, 0
	s_add_u32 s58, s58, 0x1000
	s_addc_u32 s59, s59, 0
	s_add_u32 s60, s60, 0x4400
	s_addc_u32 s61, s61, 0
	global_load_dword v43, v6, s[56:57]
	global_load_dword v59, v6, s[58:59]
	global_load_dwordx2 v[86:87], v7, s[60:61]
	s_add_u32 s56, s56, 0x1000
	s_addc_u32 s57, s57, 0
	s_add_u32 s58, s58, 0x1000
	s_addc_u32 s59, s59, 0
	s_add_u32 s60, s60, 0x4400
	s_addc_u32 s61, s61, 0
	global_load_dword v44, v6, s[56:57]
	global_load_dword v60, v6, s[58:59]
	global_load_dwordx2 v[88:89], v7, s[60:61]
	s_add_u32 s56, s56, 0x1000
	s_addc_u32 s57, s57, 0
	s_add_u32 s58, s58, 0x1000
	s_addc_u32 s59, s59, 0
	s_add_u32 s60, s60, 0x4400
	s_addc_u32 s61, s61, 0
	global_load_dword v45, v6, s[56:57]
	global_load_dword v61, v6, s[58:59]
	global_load_dwordx2 v[90:91], v7, s[60:61]
	s_add_u32 s56, s56, 0x1000
	s_addc_u32 s57, s57, 0
	s_add_u32 s58, s58, 0x1000
	s_addc_u32 s59, s59, 0
	s_add_u32 s60, s60, 0x4400
	s_addc_u32 s61, s61, 0
	global_load_dword v46, v6, s[56:57]
	global_load_dword v62, v6, s[58:59]
	global_load_dwordx2 v[92:93], v7, s[60:61]
	s_add_u32 s56, s56, 0x1000
	s_addc_u32 s57, s57, 0
	s_add_u32 s58, s58, 0x1000
	s_addc_u32 s59, s59, 0
	s_add_u32 s60, s60, 0x4400
	s_addc_u32 s61, s61, 0
	global_load_dword v47, v6, s[56:57]
	global_load_dword v63, v6, s[58:59]
	global_load_dwordx2 v[94:95], v7, s[60:61]
	s_add_u32 s56, s56, 0x1000
	s_addc_u32 s57, s57, 0
	s_add_u32 s58, s58, 0x1000
	s_addc_u32 s59, s59, 0
	s_add_u32 s60, s60, 0x4400
	s_addc_u32 s61, s61, 0
	s_waitcnt vmcnt(0)
; __device__ __forceinline__ bf16_t f2bf(float f) { return (bf16_t)(cvt_pk_bf16(f, 0.f) & 0xffffu); }
; __device__ __forceinline__ void s5_assemble_w(const int TID, const int BID, const Params& p, int l) {
;     ...
;         } else { const int kk = k - 256, d = kk >> 7, ri = (kk >> 6) & 1, n = kk & 63, j = d == 0 ? t + 1 : 16 - t;
;             const float cr = cre[(((size_t)(l * 2 + d) * 32 + g) * 16 + c) * 64 + n], ci = cim[(((size_t)(l * 2 + d) * 32 + g) * 16 + c) * 64 + n];
;             const f32x2 pv = pw[((size_t)(g * 2 + d) * 17 + j) * 64 + n];
;             val = ri == 0 ? cr * pv.x - ci * pv.y : -(cr * pv.y + ci * pv.x); }
;         wmat[idx] = f2bf(val);
	v_cndmask_b32_e64 v8, v64, v65, s[46:47]
	v_cndmask_b32_e64 v9, v65, v64, s[46:47]
	v_mul_f32_e32 v8, v32, v8
	v_mul_f32_e32 v9, v48, v9
	v_xor_b32_e32 v8, s62, v8
	v_sub_f32_e32 v8, v8, v9
	v_cvt_pk_bf16_f32 v32, v8, v183
	global_store_short v5, v32, s[54:55]
	s_add_u32 s54, s54, 0x40000
	s_addc_u32 s55, s55, 0
	v_cndmask_b32_e64 v8, v66, v67, s[46:47]
	v_cndmask_b32_e64 v9, v67, v66, s[46:47]
	v_mul_f32_e32 v8, v33, v8
	v_mul_f32_e32 v9, v49, v9
	v_xor_b32_e32 v8, s62, v8
	v_sub_f32_e32 v8, v8, v9
	v_cvt_pk_bf16_f32 v33, v8, v183
	global_store_short v5, v33, s[54:55]
	s_add_u32 s54, s54, 0x40000
	s_addc_u32 s55, s55, 0
	v_cndmask_b32_e64 v8, v68, v69, s[46:47]
	v_cndmask_b32_e64 v9, v69, v68, s[46:47]
	v_mul_f32_e32 v8, v34, v8
	v_mul_f32_e32 v9, v50, v9
	v_xor_b32_e32 v8, s62, v8
	v_sub_f32_e32 v8, v8, v9
	v_cvt_pk_bf16_f32 v34, v8, v183
	global_store_short v5, v34, s[54:55]
	s_add_u32 s54, s54, 0x40000
	s_addc_u32 s55, s55, 0
	v_cndmask_b32_e64 v8, v70, v71, s[46:47]
	v_cndmask_b32_e64 v9, v71, v70, s[46:47]
	v_mul_f32_e32 v8, v35, v8
	v_mul_f32_e32 v9, v51, v9
	v_xor_b32_e32 v8, s62, v8
	v_sub_f32_e32 v8, v8, v9
	v_cvt_pk_bf16_f32 v35, v8, v183
	global_store_short v5, v35, s[54:55]
	s_add_u32 s54, s54, 0x40000
	s_addc_u32 s55, s55, 0
	v_cndmask_b32_e64 v8, v72, v73, s[46:47]
	v_cndmask_b32_e64 v9, v73, v72, s[46:47]
	v_mul_f32_e32 v8, v36, v8
	v_mul_f32_e32 v9, v52, v9
	v_xor_b32_e32 v8, s62, v8
	v_sub_f32_e32 v8, v8, v9
	v_cvt_pk_bf16_f32 v36, v8, v183
	global_store_short v5, v36, s[54:55]
	s_add_u32 s54, s54, 0x40000
	s_addc_u32 s55, s55, 0
	v_cndmask_b32_e64 v8, v74, v75, s[46:47]
	v_cndmask_b32_e64 v9, v75, v74, s[46:47]
	v_mul_f32_e32 v8, v37, v8
	v_mul_f32_e32 v9, v53, v9
	v_xor_b32_e32 v8, s62, v8
	v_sub_f32_e32 v8, v8, v9
	v_cvt_pk_bf16_f32 v37, v8, v183
	global_store_short v5, v37, s[54:55]
	s_add_u32 s54, s54, 0x40000
	s_addc_u32 s55, s55, 0
	v_cndmask_b32_e64 v8, v76, v77, s[46:47]
	v_cndmask_b32_e64 v9, v77, v76, s[46:47]
	v_mul_f32_e32 v8, v38, v8
	v_mul_f32_e32 v9, v54, v9
	v_xor_b32_e32 v8, s62, v8
	v_sub_f32_e32 v8, v8, v9
	v_cvt_pk_bf16_f32 v38, v8, v183
	global_store_short v5, v38, s[54:55]
	s_add_u32 s54, s54, 0x40000
	s_addc_u32 s55, s55, 0
	v_cndmask_b32_e64 v8, v78, v79, s[46:47]
	v_cndmask_b32_e64 v9, v79, v78, s[46:47]
	v_mul_f32_e32 v8, v39, v8
	v_mul_f32_e32 v9, v55, v9
	v_xor_b32_e32 v8, s62, v8
	v_sub_f32_e32 v8, v8, v9
	v_cvt_pk_bf16_f32 v39, v8, v183
	global_store_short v5, v39, s[54:55]
	s_add_u32 s54, s54, 0x40000
	s_addc_u32 s55, s55, 0
	v_cndmask_b32_e64 v8, v80, v81, s[46:47]
	v_cndmask_b32_e64 v9, v81, v80, s[46:47]
	v_mul_f32_e32 v8, v40, v8
	v_mul_f32_e32 v9, v56, v9
	v_xor_b32_e32 v8, s62, v8
	v_sub_f32_e32 v8, v8, v9
	v_cvt_pk_bf16_f32 v40, v8, v183
	global_store_short v5, v40, s[54:55]
	s_add_u32 s54, s54, 0x40000
	s_addc_u32 s55, s55, 0
	v_cndmask_b32_e64 v8, v82, v83, s[46:47]
	v_cndmask_b32_e64 v9, v83, v82, s[46:47]
	v_mul_f32_e32 v8, v41, v8
	v_mul_f32_e32 v9, v57, v9
	v_xor_b32_e32 v8, s62, v8
	v_sub_f32_e32 v8, v8, v9
	v_cvt_pk_bf16_f32 v41, v8, v183
	global_store_short v5, v41, s[54:55]
	s_add_u32 s54, s54, 0x40000
	s_addc_u32 s55, s55, 0
	v_cndmask_b32_e64 v8, v84, v85, s[46:47]
	v_cndmask_b32_e64 v9, v85, v84, s[46:47]
	v_mul_f32_e32 v8, v42, v8
	v_mul_f32_e32 v9, v58, v9
	v_xor_b32_e32 v8, s62, v8
	v_sub_f32_e32 v8, v8, v9
	v_cvt_pk_bf16_f32 v42, v8, v183
	global_store_short v5, v42, s[54:55]
	s_add_u32 s54, s54, 0x40000
	s_addc_u32 s55, s55, 0
	v_cndmask_b32_e64 v8, v86, v87, s[46:47]
	v_cndmask_b32_e64 v9, v87, v86, s[46:47]
	v_mul_f32_e32 v8, v43, v8
	v_mul_f32_e32 v9, v59, v9
	v_xor_b32_e32 v8, s62, v8
	v_sub_f32_e32 v8, v8, v9
	v_cvt_pk_bf16_f32 v43, v8, v183
	global_store_short v5, v43, s[54:55]
	s_add_u32 s54, s54, 0x40000
	s_addc_u32 s55, s55, 0
	v_cndmask_b32_e64 v8, v88, v89, s[46:47]
	v_cndmask_b32_e64 v9, v89, v88, s[46:47]
	v_mul_f32_e32 v8, v44, v8
	v_mul_f32_e32 v9, v60, v9
	v_xor_b32_e32 v8, s62, v8
	v_sub_f32_e32 v8, v8, v9
	v_cvt_pk_bf16_f32 v44, v8, v183
	global_store_short v5, v44, s[54:55]
	s_add_u32 s54, s54, 0x40000
	s_addc_u32 s55, s55, 0
	v_cndmask_b32_e64 v8, v90, v91, s[46:47]
	v_cndmask_b32_e64 v9, v91, v90, s[46:47]
	v_mul_f32_e32 v8, v45, v8
	v_mul_f32_e32 v9, v61, v9
	v_xor_b32_e32 v8, s62, v8
	v_sub_f32_e32 v8, v8, v9
	v_cvt_pk_bf16_f32 v45, v8, v183
	global_store_short v5, v45, s[54:55]
	s_add_u32 s54, s54, 0x40000
	s_addc_u32 s55, s55, 0
	v_cndmask_b32_e64 v8, v92, v93, s[46:47]
	v_cndmask_b32_e64 v9, v93, v92, s[46:47]
	v_mul_f32_e32 v8, v46, v8
	v_mul_f32_e32 v9, v62, v9
	v_xor_b32_e32 v8, s62, v8
	v_sub_f32_e32 v8, v8, v9
	v_cvt_pk_bf16_f32 v46, v8, v183
	global_store_short v5, v46, s[54:55]
	s_add_u32 s54, s54, 0x40000
	s_addc_u32 s55, s55, 0
	v_cndmask_b32_e64 v8, v94, v95, s[46:47]
	v_cndmask_b32_e64 v9, v95, v94, s[46:47]
	v_mul_f32_e32 v8, v47, v8
	v_mul_f32_e32 v9, v63, v9
	v_xor_b32_e32 v8, s62, v8
	v_sub_f32_e32 v8, v8, v9
	v_cvt_pk_bf16_f32 v47, v8, v183
	global_store_short v5, v47, s[54:55]
	s_add_u32 s54, s54, 0x40000
	s_addc_u32 s55, s55, 0
	s_branch .LBB0_1022
